# phase 11: tile loader via global_load_lds into XOR-swizzled conflict-free K / V^T LDS images (no register staging, no ds_write), triple-buffered K fragment reads
# speedup vs baseline: 1.0022x; 1.0022x over previous
; __device__ __forceinline__ void phase_na(const Params& p, unsigned char* lds) {
;     const int tid = threadIdx.x, lane = tid & 63, w = __builtin_amdgcn_readfirstlane(tid >> 6), fr = lane & 15, fq = lane >> 4;
;     bf16_t* KtB = (bf16_t*)(lds + NA_KT); bf16_t* vtB = (bf16_t*)(lds + NA_VT); bf16_t* Pw = (bf16_t*)(lds + NA_PW) + w * (32 * 72); float* rbt = (float*)(lds + NA_RB);
;     const bf16_t* QK = (const bf16_t*)(p.ws + WS_P); const bf16_t* VTg = (const bf16_t*)(p.ws + WS_VT); bf16_t* O = (bf16_t*)(p.ws + WS_A);
;     const int key = tid >> 3, part = tid & 7;
;     const int vd = tid >> 2, vc4 = tid & 3;
;     const float scale = 0.08838834764831845f * 1.4426950408889634f;
;     for (int u = blockIdx.x; u < 1024; u += gridDim.x) {
;         const int r4 = u & 15, h = (u >> 4) & 15, b = u >> 8, r0 = 4 * r4;
;         const int rs_lo = min(max(r0 - 4, 0), 56), rs_hi = min(max(r0 - 1, 0), 56);
;         const int ntile = 4 + (rs_hi + 8 - rs_lo);
;         const int qr = r0 + (w >> 1), qc0 = 32 * (w & 1);
;         const int rsq = min(max(qr - 4, 0), 56);
;         __syncthreads();
;         for (int e = tid; e < 465; e += 512) rbt[e] = p.rel_bias[h * 465 + e] * 1.4426950408889634f;
;         bf16x8 aq[2][4];
; #pragma unroll
;         for (int mt = 0; mt < 2; ++mt) { const bf16_t* qp = QK + (size_t)(b * SEQ + qr * 64 + qc0 + 16 * mt + fr) * NQK + h * 128 + fq * 8;
; #pragma unroll
;             for (int ks = 0; ks < 4; ++ks) aq[mt][ks] = *(const bf16x8*)(qp + ks * 32); }
;         f32x4 Oa[2][8];
; #pragma unroll
;         for (int mt = 0; mt < 2; ++mt)
; #pragma unroll
;             for (int dt = 0; dt < 8; ++dt) Oa[mt][dt] = (f32x4){0.f, 0.f, 0.f, 0.f};
;         float mrow[2] = {-1e30f, -1e30f}, lrow[2] = {0.f, 0.f};
;         u32x4 ra[4];
;     ...
;                     const int c = qc0 + 16 * mt + fr; const int cs = min(max(c - 8, 0), 48); const int wlo = mt ? wlo1 : wlo0, whi = mt ? whi1 : whi0;
;                     float mx = -1e30f;
; #pragma unroll
;                     for (int nt = 0; nt < 4; ++nt) {
;                         const bool act = !band || (16 * nt < whi && 16 * nt + 16 > wlo);
;                         if (act) {
; #pragma unroll
;                             for (int j = 0; j < 4; ++j) { float v = st[mt][nt][j] * scale;
.Lna_begin:
	v_readfirstlane_b32 s10, v162
	s_add_u32 s4, s90, 0x10a00000
	s_addc_u32 s5, s91, 0
	s_add_u32 s6, s90, 0x19c00000
	s_addc_u32 s7, s91, 0
	s_add_u32 s8, s90, 0xc600000
	s_addc_u32 s9, s91, 0
	s_lshr_b32 s10, s10, 6
	s_lshr_b32 s11, s10, 1
	s_and_b32 s12, s10, 1
	s_lshl_b32 s12, s12, 5
	s_mov_b32 s30, 0x3e0293ee
	s_mov_b32 s31, 0xf149f2ca
	v_and_b32_e32 v232, 63, v162
	v_and_b32_e32 v233, 15, v232
	v_lshrrev_b32_e32 v234, 4, v232
	v_lshrrev_b32_e32 v235, 3, v162
	v_and_b32_e32 v236, 7, v162
	v_lshlrev_b32_e32 v237, 5, v236
	v_lshl_or_b32 v163, v235, 13, v237
	v_mul_u32_u24_e32 v238, 0x110, v235
	v_add_u32_e32 v164, v238, v237
	v_lshrrev_b32_e32 v235, 2, v162
	v_and_b32_e32 v236, 3, v162
	v_lshlrev_b32_e32 v237, 5, v236
	v_mul_u32_u24_e32 v238, 0x8800, v235
	v_add_u32_e32 v165, v238, v237
	v_mul_u32_u24_e32 v238, 0x90, v235
	v_add_u32_e32 v238, v238, v237
	v_add_u32_e32 v166, 52224, v238
	v_mul_u32_u24_e32 v238, 0x110, v233
	v_lshl_add_u32 v167, v234, 4, v238
	v_mul_u32_u24_e32 v238, 0x90, v233
	v_lshl_add_u32 v238, v234, 3, v238
	v_add_u32_e32 v168, 52224, v238
	v_xor_b32_e32 v235, 16, v232
	v_lshlrev_b32_e32 v218, 2, v235
	v_xor_b32_e32 v235, 32, v232
	v_lshlrev_b32_e32 v219, 2, v235
	s_lshl_b32 s69, s10, 11
	v_lshrrev_b32_e32 v235, 4, v232
	s_lshl_b32 s0, s10, 3
	s_add_i32 s0, s0, 0
	v_add_u32_e32 v235, s0, v235
	v_and_b32_e32 v236, 15, v235
	v_and_b32_e32 v237, 15, v232
	v_xor_b32_e32 v236, v236, v237
	v_lshlrev_b32_e32 v236, 4, v236
	v_lshl_add_u32 v163, v235, 13, v236
	v_lshrrev_b32_e32 v235, 4, v232
	s_lshl_b32 s0, s10, 3
	s_add_i32 s0, s0, 4
	v_add_u32_e32 v235, s0, v235
	v_and_b32_e32 v236, 15, v235
	v_and_b32_e32 v237, 15, v232
	v_xor_b32_e32 v236, v236, v237
	v_lshlrev_b32_e32 v236, 4, v236
	v_lshl_add_u32 v164, v235, 13, v236
	v_lshrrev_b32_e32 v235, 3, v232
	s_lshl_b32 s0, s10, 4
	s_add_i32 s0, s0, 0
	v_add_u32_e32 v235, s0, v235
	v_bfe_u32 v236, v235, 1, 3
	v_and_b32_e32 v237, 7, v232
	v_xor_b32_e32 v236, v236, v237
	v_lshlrev_b32_e32 v236, 4, v236
	v_mul_u32_u24_e32 v237, 0x8800, v235
	v_add_u32_e32 v165, v237, v236
	v_lshrrev_b32_e32 v235, 3, v232
	s_lshl_b32 s0, s10, 4
	s_add_i32 s0, s0, 8
	v_add_u32_e32 v235, s0, v235
	v_bfe_u32 v236, v235, 1, 3
	v_and_b32_e32 v237, 7, v232
	v_xor_b32_e32 v236, v236, v237
	v_lshlrev_b32_e32 v236, 4, v236
	v_mul_u32_u24_e32 v237, 0x8800, v235
	v_add_u32_e32 v166, v237, v236
	v_add_u32_e32 v235, 0, v234
	v_xor_b32_e32 v235, v235, v233
	v_lshlrev_b32_e32 v235, 4, v235
	v_lshl_add_u32 v170, v233, 8, v235
	v_add_u32_e32 v235, 4, v234
	v_xor_b32_e32 v235, v235, v233
	v_lshlrev_b32_e32 v235, 4, v235
	v_lshl_add_u32 v171, v233, 8, v235
	v_add_u32_e32 v235, 8, v234
	v_xor_b32_e32 v235, v235, v233
	v_lshlrev_b32_e32 v235, 4, v235
	v_lshl_add_u32 v172, v233, 8, v235
	v_add_u32_e32 v235, 12, v234
	v_xor_b32_e32 v235, v235, v233
	v_lshlrev_b32_e32 v235, 4, v235
	v_lshl_add_u32 v173, v233, 8, v235
	v_lshrrev_b32_e32 v235, 1, v234
	v_add_u32_e32 v235, 0, v235
	v_bfe_u32 v236, v233, 1, 3
	v_xor_b32_e32 v235, v235, v236
	v_lshlrev_b32_e32 v235, 4, v235
	v_lshl_add_u32 v235, v233, 7, v235
	v_and_b32_e32 v236, 1, v234
	v_lshl_add_u32 v235, v236, 3, v235
	v_add_u32_e32 v174, 49152, v235
	v_lshrrev_b32_e32 v235, 1, v234
	v_add_u32_e32 v235, 2, v235
	v_bfe_u32 v236, v233, 1, 3
	v_xor_b32_e32 v235, v235, v236
	v_lshlrev_b32_e32 v235, 4, v235
	v_lshl_add_u32 v235, v233, 7, v235
	v_and_b32_e32 v236, 1, v234
	v_lshl_add_u32 v235, v236, 3, v235
	v_add_u32_e32 v175, 49152, v235
	v_lshrrev_b32_e32 v235, 1, v234
	v_add_u32_e32 v235, 4, v235
	v_bfe_u32 v236, v233, 1, 3
	v_xor_b32_e32 v235, v235, v236
	v_lshlrev_b32_e32 v235, 4, v235
	v_lshl_add_u32 v235, v233, 7, v235
	v_and_b32_e32 v236, 1, v234
	v_lshl_add_u32 v235, v236, 3, v235
	v_add_u32_e32 v176, 49152, v235
	v_lshrrev_b32_e32 v235, 1, v234
	v_add_u32_e32 v235, 6, v235
	v_bfe_u32 v236, v233, 1, 3
	v_xor_b32_e32 v235, v235, v236
	v_lshlrev_b32_e32 v235, 4, v235
	v_lshl_add_u32 v235, v233, 7, v235
	v_and_b32_e32 v236, 1, v234
	v_lshl_add_u32 v235, v236, 3, v235
	v_add_u32_e32 v177, 49152, v235
	v_mov_b32_e32 v232, 0
	v_mov_b32_e32 v239, 0xf149f2ca
	v_add_u32_e32 v235, s12, v233
	v_sub_u32_e64 v236, v235, 8 clamp
	v_min_u32_e32 v236, 48, v236
	v_lshlrev_b32_e32 v237, 2, v234
	v_sub_u32_e32 v238, v237, v235
	v_lshlrev_b32_e32 v238, 2, v238
	v_add_u32_e32 v220, 110908, v238
	v_sub_u32_e32 v238, v237, v236
	v_add_u32_e32 v237, 0, v238
	v_cmp_gt_u32_e32 vcc, 16, v237
	v_cndmask_b32_e32 v186, v239, v232, vcc
	v_add_u32_e32 v237, 1, v238
	v_cmp_gt_u32_e32 vcc, 16, v237
	v_cndmask_b32_e32 v187, v239, v232, vcc
	v_add_u32_e32 v237, 2, v238
	v_cmp_gt_u32_e32 vcc, 16, v237
	v_cndmask_b32_e32 v188, v239, v232, vcc
	v_add_u32_e32 v237, 3, v238
	v_cmp_gt_u32_e32 vcc, 16, v237
	v_cndmask_b32_e32 v189, v239, v232, vcc
	v_add_u32_e32 v237, 16, v238
	v_cmp_gt_u32_e32 vcc, 16, v237
	v_cndmask_b32_e32 v190, v239, v232, vcc
	v_add_u32_e32 v237, 17, v238
	v_cmp_gt_u32_e32 vcc, 16, v237
	v_cndmask_b32_e32 v191, v239, v232, vcc
	v_add_u32_e32 v237, 18, v238
	v_cmp_gt_u32_e32 vcc, 16, v237
	v_cndmask_b32_e32 v192, v239, v232, vcc
	v_add_u32_e32 v237, 19, v238
	v_cmp_gt_u32_e32 vcc, 16, v237
	v_cndmask_b32_e32 v193, v239, v232, vcc
	v_add_u32_e32 v237, 32, v238
	v_cmp_gt_u32_e32 vcc, 16, v237
	v_cndmask_b32_e32 v194, v239, v232, vcc
	v_add_u32_e32 v237, 33, v238
	v_cmp_gt_u32_e32 vcc, 16, v237
	v_cndmask_b32_e32 v195, v239, v232, vcc
	v_add_u32_e32 v237, 34, v238
	v_cmp_gt_u32_e32 vcc, 16, v237
	v_cndmask_b32_e32 v196, v239, v232, vcc
	v_add_u32_e32 v237, 35, v238
	v_cmp_gt_u32_e32 vcc, 16, v237
	v_cndmask_b32_e32 v197, v239, v232, vcc
	v_add_u32_e32 v237, 48, v238
; #define NA_WRITE(R, buf) do { bf16_t* kd = KtB + (buf) * (64 * 136) + key * 136 + part * 16; bf16_t* vdp = vtB + (buf) * (128 * 72) + vd * 72 + vc4 * 16; \
;         *(u32x4*)kd = R[0]; *(u32x4*)(kd + 8) = R[1]; *(u32x4*)vdp = R[2]; *(u32x4*)(vdp + 8) = R[3]; } while (0)
; __device__ __forceinline__ void phase_na(const Params& p, unsigned char* lds) {
;     ...
;     for (int u = blockIdx.x; u < 1024; u += gridDim.x) {
;         const int r4 = u & 15, h = (u >> 4) & 15, b = u >> 8, r0 = 4 * r4;
;         const int rs_lo = min(max(r0 - 4, 0), 56), rs_hi = min(max(r0 - 1, 0), 56);
;         const int ntile = 4 + (rs_hi + 8 - rs_lo);
;         const int qr = r0 + (w >> 1), qc0 = 32 * (w & 1);
;         const int rsq = min(max(qr - 4, 0), 56);
;         __syncthreads();
;         for (int e = tid; e < 465; e += 512) rbt[e] = p.rel_bias[h * 465 + e] * 1.4426950408889634f;
;         bf16x8 aq[2][4];
; #pragma unroll
;         for (int mt = 0; mt < 2; ++mt) { const bf16_t* qp = QK + (size_t)(b * SEQ + qr * 64 + qc0 + 16 * mt + fr) * NQK + h * 128 + fq * 8;
; #pragma unroll
;             for (int ks = 0; ks < 4; ++ks) aq[mt][ks] = *(const bf16x8*)(qp + ks * 32); }
;     ...
;         { u32x4 rn[4];
;           NA_LOAD(ra, 0); NA_LOAD(rn, 1); NA_WRITE(ra, 0);
;           ra[0] = rn[0]; ra[1] = rn[1]; ra[2] = rn[2]; ra[3] = rn[3]; }
	v_cmp_gt_u32_e32 vcc, 16, v237
	v_cndmask_b32_e32 v198, v239, v232, vcc
	v_add_u32_e32 v237, 49, v238
	v_cmp_gt_u32_e32 vcc, 16, v237
	v_cndmask_b32_e32 v199, v239, v232, vcc
	v_add_u32_e32 v237, 50, v238
	v_cmp_gt_u32_e32 vcc, 16, v237
	v_cndmask_b32_e32 v200, v239, v232, vcc
	v_add_u32_e32 v237, 51, v238
	v_cmp_gt_u32_e32 vcc, 16, v237
	v_cndmask_b32_e32 v201, v239, v232, vcc
	v_add_u32_e32 v235, s12, v233
	v_add_u32_e32 v235, 16, v235
	v_sub_u32_e64 v236, v235, 8 clamp
	v_min_u32_e32 v236, 48, v236
	v_lshlrev_b32_e32 v237, 2, v234
	v_sub_u32_e32 v238, v237, v235
	v_lshlrev_b32_e32 v238, 2, v238
	v_add_u32_e32 v221, 110908, v238
	v_sub_u32_e32 v238, v237, v236
	v_add_u32_e32 v237, 0, v238
	v_cmp_gt_u32_e64 s[32:33], 16, v237
	v_add_u32_e32 v237, 1, v238
	v_cmp_gt_u32_e64 s[34:35], 16, v237
	v_add_u32_e32 v237, 2, v238
	v_cmp_gt_u32_e64 s[36:37], 16, v237
	v_add_u32_e32 v237, 3, v238
	v_cmp_gt_u32_e64 s[38:39], 16, v237
	v_add_u32_e32 v237, 16, v238
	v_cmp_gt_u32_e64 s[40:41], 16, v237
	v_add_u32_e32 v237, 17, v238
	v_cmp_gt_u32_e64 s[42:43], 16, v237
	v_add_u32_e32 v237, 18, v238
	v_cmp_gt_u32_e64 s[44:45], 16, v237
	v_add_u32_e32 v237, 19, v238
	v_cmp_gt_u32_e64 s[46:47], 16, v237
	v_add_u32_e32 v237, 32, v238
	v_cmp_gt_u32_e64 s[48:49], 16, v237
	v_add_u32_e32 v237, 33, v238
	v_cmp_gt_u32_e64 s[50:51], 16, v237
	v_add_u32_e32 v237, 34, v238
	v_cmp_gt_u32_e64 s[52:53], 16, v237
	v_add_u32_e32 v237, 35, v238
	v_cmp_gt_u32_e64 s[54:55], 16, v237
	v_add_u32_e32 v237, 48, v238
	v_cmp_gt_u32_e64 s[56:57], 16, v237
	v_add_u32_e32 v237, 49, v238
	v_cmp_gt_u32_e64 s[58:59], 16, v237
	v_add_u32_e32 v237, 50, v238
	v_cmp_gt_u32_e64 s[60:61], 16, v237
	v_add_u32_e32 v237, 51, v238
	v_cmp_gt_u32_e64 s[62:63], 16, v237
	v_lshlrev_b32_e32 v235, 2, v162
	v_add_u32_e32 v235, 110592, v235
	v_mov_b32_e32 v236, 0
	ds_write_b32 v235, v236
	v_cmp_gt_u32_e32 vcc, 128, v162
	s_and_saveexec_b64 s[0:1], vcc
	ds_write_b32 v235, v236 offset:2048
	s_mov_b64 exec, s[0:1]
	s_mov_b32 s13, s92
	s_waitcnt lgkmcnt(0)
.Lna_unit:
	s_cmp_ge_u32 s13, 0x400
	s_cbranch_scc1 .Lna_done
	s_lshr_b32 s15, s13, 8
	s_and_b32 s0, s13, 7
	s_bfe_u32 s1, s13, 0x50003
	s_lshr_b32 s14, s1, 4
	s_lshl_b32 s0, s0, 1
	s_or_b32 s14, s14, s0
	s_and_b32 s16, s1, 15
	s_lshl_b32 s16, s16, 2
	s_add_i32 s17, s16, -4
	s_max_i32 s17, s17, 0
	s_min_i32 s17, s17, 56
	s_add_i32 s18, s16, -1
	s_max_i32 s18, s18, 0
	s_min_i32 s18, s18, 56
	s_sub_i32 s18, s18, s17
	s_add_i32 s18, s18, 12
	s_add_i32 s19, s16, s11
	s_add_i32 s20, s19, -4
	s_max_i32 s20, s20, 0
	s_min_i32 s20, s20, 56
	s_barrier
	s_movk_i32 s0, 0x1d1
	v_cmp_gt_u32_e32 vcc, s0, v162
	s_and_saveexec_b64 s[2:3], vcc
	s_mul_i32 s0, s14, 0x1d1
	v_add_lshl_u32 v232, s0, v162, 2
	global_load_dword v234, v232, s[84:85]
	s_mov_b64 exec, s[2:3]
	s_mov_b32 s21, 0
	s_lshl_b32 s28, s15, 8
	s_add_i32 s28, s28, 0x4000
	s_lshl_b32 s29, s21, 6
	s_add_i32 s28, s28, s29
	s_add_i32 s29, s21, s17
	s_add_i32 s29, s29, -4
	s_lshl_b32 s29, s29, 6
	s_lshl_b32 s26, s15, 12
	s_add_i32 s29, s29, s26
	s_cmp_lt_u32 s21, 4
	s_cselect_b32 s28, s28, s29
	s_lshl_b32 s26, s28, 13
	s_lshl_b32 s29, s14, 8
	s_add_i32 s26, s26, s29
	s_add_i32 s26, s26, 0x1000
	s_lshl_b32 s27, s28, 1
	s_mul_i32 s29, s14, 0x440000
	s_add_i32 s27, s27, s29
	s_mov_b32 s75, 0
	s_add_u32 s70, s4, s26
	s_addc_u32 s71, s5, 0
	s_add_u32 s72, s6, s27
	s_addc_u32 s73, s7, 0
	s_lshl_b32 s74, s75, 14
	s_add_i32 s74, s74, s69
	s_mov_b32 m0, s74
	s_nop 0
	global_load_lds_dwordx4 v163, s[70:71]
	s_add_i32 m0, s74, 0x400
	s_nop 0
	global_load_lds_dwordx4 v164, s[70:71]
	s_add_i32 m0, s74, 49152
	s_nop 0
	global_load_lds_dwordx4 v165, s[72:73]
	s_add_i32 m0, s74, 50176
	s_nop 0
	global_load_lds_dwordx4 v166, s[72:73]
	s_lshl_b32 s0, s15, 12
	s_lshl_b32 s1, s19, 6
	s_add_i32 s0, s0, s1
	s_add_i32 s0, s0, s12
	v_and_b32_e32 v232, 15, v162
	v_bfe_u32 v233, v162, 4, 2
	v_add_u32_e32 v232, s0, v232
	v_lshlrev_b32_e32 v232, 13, v232
	v_lshl_add_u32 v232, v233, 4, v232
	s_lshl_b32 s1, s14, 8
	v_add_u32_e32 v232, s1, v232
	v_add_u32_e32 v233, 0x20000, v232
	global_load_dwordx4 v[0:3], v232, s[4:5] offset:0
	global_load_dwordx4 v[4:7], v232, s[4:5] offset:64
	global_load_dwordx4 v[8:11], v232, s[4:5] offset:128
	global_load_dwordx4 v[12:15], v232, s[4:5] offset:192
	global_load_dwordx4 v[16:19], v233, s[4:5] offset:0
	global_load_dwordx4 v[20:23], v233, s[4:5] offset:64
	global_load_dwordx4 v[24:27], v233, s[4:5] offset:128
	global_load_dwordx4 v[28:31], v233, s[4:5] offset:192
	s_mov_b32 s21, 1
	s_lshl_b32 s28, s15, 8
	s_add_i32 s28, s28, 0x4000
	s_lshl_b32 s29, s21, 6
	s_add_i32 s28, s28, s29
	s_add_i32 s29, s21, s17
	s_add_i32 s29, s29, -4
	s_lshl_b32 s29, s29, 6
	s_lshl_b32 s26, s15, 12
	s_add_i32 s29, s29, s26
	s_cmp_lt_u32 s21, 4
	s_cselect_b32 s28, s28, s29
	s_lshl_b32 s26, s28, 13
	s_lshl_b32 s29, s14, 8
	s_add_i32 s26, s26, s29
	s_add_i32 s26, s26, 0x1000
	s_lshl_b32 s27, s28, 1
	s_mul_i32 s29, s14, 0x440000
	s_add_i32 s27, s27, s29
	s_mov_b32 s75, 1
	s_add_u32 s70, s4, s26
	s_addc_u32 s71, s5, 0
	s_add_u32 s72, s6, s27
	s_addc_u32 s73, s7, 0
	s_lshl_b32 s74, s75, 14
	s_add_i32 s74, s74, s69
	s_mov_b32 m0, s74
	s_nop 0
	global_load_lds_dwordx4 v163, s[70:71]
	s_add_i32 m0, s74, 0x400
	s_nop 0
	global_load_lds_dwordx4 v164, s[70:71]
	s_add_i32 m0, s74, 49152
	s_nop 0
	global_load_lds_dwordx4 v165, s[72:73]
	s_add_i32 m0, s74, 50176
	s_nop 0
	global_load_lds_dwordx4 v166, s[72:73]
	v_mov_b32_e32 v32, 0
	v_mov_b32_e32 v33, 0
	v_mov_b32_e32 v34, 0
	v_mov_b32_e32 v35, 0
	v_mov_b32_e32 v36, 0
	v_mov_b32_e32 v37, 0
	v_mov_b32_e32 v38, 0
	v_mov_b32_e32 v39, 0
	v_mov_b32_e32 v40, 0
	v_mov_b32_e32 v41, 0
	v_mov_b32_e32 v42, 0
; #define NA_WRITE(R, buf) do { bf16_t* kd = KtB + (buf) * (64 * 136) + key * 136 + part * 16; bf16_t* vdp = vtB + (buf) * (128 * 72) + vd * 72 + vc4 * 16; \
;         *(u32x4*)kd = R[0]; *(u32x4*)(kd + 8) = R[1]; *(u32x4*)vdp = R[2]; *(u32x4*)(vdp + 8) = R[3]; } while (0)
; __device__ __forceinline__ void phase_na(const Params& p, unsigned char* lds) {
;     ...
;         f32x4 Oa[2][8];
; #pragma unroll
;         for (int mt = 0; mt < 2; ++mt)
; #pragma unroll
;             for (int dt = 0; dt < 8; ++dt) Oa[mt][dt] = (f32x4){0.f, 0.f, 0.f, 0.f};
;         float mrow[2] = {-1e30f, -1e30f}, lrow[2] = {0.f, 0.f};
;         u32x4 ra[4];
;     ...
;         { u32x4 rn[4];
;           NA_LOAD(ra, 0); NA_LOAD(rn, 1); NA_WRITE(ra, 0);
;           ra[0] = rn[0]; ra[1] = rn[1]; ra[2] = rn[2]; ra[3] = rn[3]; }
;         __syncthreads();
;         for (int kt = 0; kt < ntile; ++kt) {
;             if (kt + 1 < ntile) { NA_WRITE(ra, (kt + 1) & 1); if (kt + 2 < ntile) NA_LOAD(ra, kt + 2); }
;             const bool band = kt >= 4; const int kr = rs_lo + kt - 4;
;             if (!(band && (kr < rsq || kr >= rsq + 8))) {
;                 const bf16_t* Kt = KtB + (kt & 1) * (64 * 136); const bf16_t* vt = vtB + (kt & 1) * (128 * 72);
;                 f32x4 st[2][4];
;                 const int wlo0 = min(max(qc0 - 8, 0), 48), whi0 = min(max(qc0 + 7, 0), 48) + 16, wlo1 = min(max(qc0 + 8, 0), 48), whi1 = min(max(qc0 + 23, 0), 48) + 16;
; #pragma unroll
;                 for (int nt = 0; nt < 4; ++nt) {
;                     const bool act0 = !band || (16 * nt < whi0 && 16 * nt + 16 > wlo0), act1 = !band || (16 * nt < whi1 && 16 * nt + 16 > wlo1);
;                     st[0][nt] = (f32x4){0.f, 0.f, 0.f, 0.f}; st[1][nt] = (f32x4){0.f, 0.f, 0.f, 0.f};
;                     if (act0 || act1) {
;                         bf16x8 Bk[4];
; #pragma unroll
;                         for (int ks = 0; ks < 4; ++ks) Bk[ks] = *(const bf16x8*)(Kt + (nt * 16 + fr) * 136 + ks * 32 + fq * 8);
; #pragma unroll
;                         for (int ks = 0; ks < 4; ++ks) {
;                             if (act0) st[0][nt] = __builtin_amdgcn_mfma_f32_16x16x32_bf16(Bk[ks], aq[0][ks], st[0][nt], 0, 0, 0);
;                             if (act1) st[1][nt] = __builtin_amdgcn_mfma_f32_16x16x32_bf16(Bk[ks], aq[1][ks], st[1][nt], 0, 0, 0); }
	v_mov_b32_e32 v43, 0
	v_mov_b32_e32 v44, 0
	v_mov_b32_e32 v45, 0
	v_mov_b32_e32 v46, 0
	v_mov_b32_e32 v47, 0
	v_mov_b32_e32 v48, 0
	v_mov_b32_e32 v49, 0
	v_mov_b32_e32 v50, 0
	v_mov_b32_e32 v51, 0
	v_mov_b32_e32 v52, 0
	v_mov_b32_e32 v53, 0
	v_mov_b32_e32 v54, 0
	v_mov_b32_e32 v55, 0
	v_mov_b32_e32 v56, 0
	v_mov_b32_e32 v57, 0
	v_mov_b32_e32 v58, 0
	v_mov_b32_e32 v59, 0
	v_mov_b32_e32 v60, 0
	v_mov_b32_e32 v61, 0
	v_mov_b32_e32 v62, 0
	v_mov_b32_e32 v63, 0
	v_mov_b32_e32 v64, 0
	v_mov_b32_e32 v65, 0
	v_mov_b32_e32 v66, 0
	v_mov_b32_e32 v67, 0
	v_mov_b32_e32 v68, 0
	v_mov_b32_e32 v69, 0
	v_mov_b32_e32 v70, 0
	v_mov_b32_e32 v71, 0
	v_mov_b32_e32 v72, 0
	v_mov_b32_e32 v73, 0
	v_mov_b32_e32 v74, 0
	v_mov_b32_e32 v75, 0
	v_mov_b32_e32 v76, 0
	v_mov_b32_e32 v77, 0
	v_mov_b32_e32 v78, 0
	v_mov_b32_e32 v79, 0
	v_mov_b32_e32 v80, 0
	v_mov_b32_e32 v81, 0
	v_mov_b32_e32 v82, 0
	v_mov_b32_e32 v83, 0
	v_mov_b32_e32 v84, 0
	v_mov_b32_e32 v85, 0
	v_mov_b32_e32 v86, 0
	v_mov_b32_e32 v87, 0
	v_mov_b32_e32 v88, 0
	v_mov_b32_e32 v89, 0
	v_mov_b32_e32 v90, 0
	v_mov_b32_e32 v91, 0
	v_mov_b32_e32 v92, 0
	v_mov_b32_e32 v93, 0
	v_mov_b32_e32 v94, 0
	v_mov_b32_e32 v95, 0
	v_mov_b32_e32 v222, 0xf149f2ca
	v_mov_b32_e32 v224, 0
	v_mov_b32_e32 v226, 0x7149f2ca
	v_mov_b32_e32 v223, 0xf149f2ca
	v_mov_b32_e32 v225, 0
	v_mov_b32_e32 v227, 0x7149f2ca
	s_movk_i32 s0, 0x1d1
	v_cmp_gt_u32_e32 vcc, s0, v162
	v_lshlrev_b32_e32 v235, 2, v162
	v_add_u32_e32 v235, 110848, v235
	s_waitcnt vmcnt(16)
	s_and_saveexec_b64 s[2:3], vcc
	v_mul_f32_e32 v234, 0x413504f3, v234
	ds_write_b32 v235, v234
	s_mov_b64 exec, s[2:3]
	s_waitcnt vmcnt(12)
	s_waitcnt lgkmcnt(0)
	s_barrier
	s_waitcnt vmcnt(4)
	s_mov_b32 s21, 0
	s_mov_b32 s65, 0
	s_mov_b32 s66, 1
.Lna_tile:
	s_add_i32 s22, s21, 2
	s_cmp_ge_u32 s22, s18
	s_cbranch_scc1 .Lna_noload
	s_lshl_b32 s28, s15, 8
	s_add_i32 s28, s28, 0x4000
	s_lshl_b32 s29, s22, 6
	s_add_i32 s28, s28, s29
	s_add_i32 s29, s22, s17
	s_add_i32 s29, s29, -4
	s_lshl_b32 s29, s29, 6
	s_lshl_b32 s26, s15, 12
	s_add_i32 s29, s29, s26
	s_cmp_lt_u32 s22, 4
	s_cselect_b32 s28, s28, s29
	s_lshl_b32 s26, s28, 13
	s_lshl_b32 s29, s14, 8
	s_add_i32 s26, s26, s29
	s_add_i32 s26, s26, 0x1000
	s_lshl_b32 s27, s28, 1
	s_mul_i32 s29, s14, 0x440000
	s_add_i32 s27, s27, s29
	s_add_i32 s75, s65, s66
	s_sub_i32 s75, 3, s75
	s_add_u32 s70, s4, s26
	s_addc_u32 s71, s5, 0
	s_add_u32 s72, s6, s27
	s_addc_u32 s73, s7, 0
	s_lshl_b32 s74, s75, 14
	s_add_i32 s74, s74, s69
	s_mov_b32 m0, s74
	s_nop 0
	global_load_lds_dwordx4 v163, s[70:71]
	s_add_i32 m0, s74, 0x400
	s_nop 0
	global_load_lds_dwordx4 v164, s[70:71]
	s_add_i32 m0, s74, 49152
	s_nop 0
	global_load_lds_dwordx4 v165, s[72:73]
	s_add_i32 m0, s74, 50176
	s_nop 0
	global_load_lds_dwordx4 v166, s[72:73]
.Lna_noload:
	s_lshl_b32 s23, s65, 14
	v_add_u32_e32 v178, s23, v170
	v_add_u32_e32 v179, s23, v171
	v_add_u32_e32 v180, s23, v172
	v_add_u32_e32 v181, s23, v173
	v_add_u32_e32 v182, s23, v174
	v_add_u32_e32 v183, s23, v175
	v_add_u32_e32 v184, s23, v176
	v_add_u32_e32 v185, s23, v177
	s_add_i32 s25, s17, s21
	s_add_i32 s25, s25, -4
	s_sub_i32 s22, s25, s20
	s_cmp_lt_u32 s21, 4
	s_cbranch_scc1 .Lna_c_ctx
	s_cmp_lt_u32 s22, 8
	s_cbranch_scc0 .Lna_after
	s_sub_i32 s22, s25, s19
	s_add_i32 s22, s22, 7
	s_mul_i32 s22, s22, 0x7c
	s_bitcmp1_b32 s10, 0
	s_cbranch_scc1 .Lna_c_band1
.Lna_c_band0:
	v_add_u32_e32 v230, s22, v220
	v_add_u32_e32 v231, s22, v221
	ds_read2_b32 v[96:97], v230 offset0:0 offset1:1
	ds_read2_b32 v[98:99], v230 offset0:2 offset1:3
	ds_read2_b32 v[100:101], v230 offset0:16 offset1:17
	ds_read2_b32 v[102:103], v230 offset0:18 offset1:19
	ds_read2_b32 v[112:113], v231 offset0:0 offset1:1
	ds_read2_b32 v[114:115], v231 offset0:2 offset1:3
	ds_read2_b32 v[116:117], v231 offset0:16 offset1:17
	ds_read2_b32 v[118:119], v231 offset0:18 offset1:19
	ds_read2_b32 v[120:121], v231 offset0:32 offset1:33
	ds_read2_b32 v[122:123], v231 offset0:34 offset1:35
	ds_read_b128 v[128:131], v178
	ds_read_b128 v[132:135], v179
	ds_read_b128 v[136:139], v180
	ds_read_b128 v[140:143], v181
	ds_read_b128 v[144:147], v178 offset:4096
	ds_read_b128 v[148:151], v179 offset:4096
	ds_read_b128 v[152:155], v180 offset:4096
	ds_read_b128 v[156:159], v181 offset:4096
	s_waitcnt lgkmcnt(8)
	v_mov_b32_e32 v232, 0xf149f2ca
	v_add_f32_e32 v96, v96, v186
	v_add_f32_e32 v97, v97, v187
	v_add_f32_e32 v98, v98, v188
	v_add_f32_e32 v99, v99, v189
	v_add_f32_e32 v100, v100, v190
	v_add_f32_e32 v101, v101, v191
	v_add_f32_e32 v102, v102, v192
	v_add_f32_e32 v103, v103, v193
	v_cndmask_b32_e64 v112, v232, v112, s[32:33]
	v_cndmask_b32_e64 v113, v232, v113, s[34:35]
	v_cndmask_b32_e64 v114, v232, v114, s[36:37]
	v_cndmask_b32_e64 v115, v232, v115, s[38:39]
	v_cndmask_b32_e64 v116, v232, v116, s[40:41]
	v_cndmask_b32_e64 v117, v232, v117, s[42:43]
	v_cndmask_b32_e64 v118, v232, v118, s[44:45]
	v_cndmask_b32_e64 v119, v232, v119, s[46:47]
	v_cndmask_b32_e64 v120, v232, v120, s[48:49]
	v_cndmask_b32_e64 v121, v232, v121, s[50:51]
	v_cndmask_b32_e64 v122, v232, v122, s[52:53]
	v_cndmask_b32_e64 v123, v232, v123, s[54:55]
	ds_read_b128 v[202:205], v178 offset:8192
	ds_read_b128 v[206:209], v179 offset:8192
	ds_read_b128 v[210:213], v180 offset:8192
	ds_read_b128 v[214:217], v181 offset:8192
	s_waitcnt lgkmcnt(8)
	v_mfma_f32_16x16x32_bf16 v[96:99], v[128:131], v[0:3], v[96:99]
	v_mfma_f32_16x16x32_bf16 v[112:115], v[128:131], v[16:19], v[112:115]
	v_mfma_f32_16x16x32_bf16 v[96:99], v[132:135], v[4:7], v[96:99]
	v_mfma_f32_16x16x32_bf16 v[112:115], v[132:135], v[20:23], v[112:115]
	v_mfma_f32_16x16x32_bf16 v[96:99], v[136:139], v[8:11], v[96:99]
	v_mfma_f32_16x16x32_bf16 v[112:115], v[136:139], v[24:27], v[112:115]
	v_mfma_f32_16x16x32_bf16 v[96:99], v[140:143], v[12:15], v[96:99]
	v_mfma_f32_16x16x32_bf16 v[112:115], v[140:143], v[28:31], v[112:115]
	s_waitcnt lgkmcnt(4)
; __device__ __forceinline__ void phase_na(const Params& p, unsigned char* lds) {
;     ...
;                 for (int nt = 0; nt < 4; ++nt) {
;                     const bool act0 = !band || (16 * nt < whi0 && 16 * nt + 16 > wlo0), act1 = !band || (16 * nt < whi1 && 16 * nt + 16 > wlo1);
;                     st[0][nt] = (f32x4){0.f, 0.f, 0.f, 0.f}; st[1][nt] = (f32x4){0.f, 0.f, 0.f, 0.f};
;                     if (act0 || act1) {
;                         bf16x8 Bk[4];
; #pragma unroll
;                         for (int ks = 0; ks < 4; ++ks) Bk[ks] = *(const bf16x8*)(Kt + (nt * 16 + fr) * 136 + ks * 32 + fq * 8);
; #pragma unroll
;                         for (int ks = 0; ks < 4; ++ks) {
;                             if (act0) st[0][nt] = __builtin_amdgcn_mfma_f32_16x16x32_bf16(Bk[ks], aq[0][ks], st[0][nt], 0, 0, 0);
;                             if (act1) st[1][nt] = __builtin_amdgcn_mfma_f32_16x16x32_bf16(Bk[ks], aq[1][ks], st[1][nt], 0, 0, 0); }
;                     }
;                 }
;                 unsigned pk[2][4][2];
; #pragma unroll
;                 for (int mt = 0; mt < 2; ++mt) {
;                     __builtin_amdgcn_sched_barrier(0);
;                     const int c = qc0 + 16 * mt + fr; const int cs = min(max(c - 8, 0), 48); const int wlo = mt ? wlo1 : wlo0, whi = mt ? whi1 : whi0;
;                     float mx = -1e30f;
; #pragma unroll
;                     for (int nt = 0; nt < 4; ++nt) {
;                         const bool act = !band || (16 * nt < whi && 16 * nt + 16 > wlo);
;                         if (act) {
; #pragma unroll
;                             for (int j = 0; j < 4; ++j) { float v = st[mt][nt][j] * scale;
;                                 if (band) { const int kc = nt * 16 + fq * 4 + j; const bool valid = kc >= cs && kc < cs + 16; const int dci = min(max(kc - c + 15, 0), 30);
;                                     v += rbt[(kr - qr + 7) * 31 + dci]; v = valid ? v : -1e30f; }
;                                 st[mt][nt][j] = v; mx = fmaxf(mx, v); }
;                         }
;                     }
;                     mx = fmaxf(mx, __shfl_xor(mx, 16)); mx = fmaxf(mx, __shfl_xor(mx, 32));
;                     const bool resc = !__all(mx - mrow[mt] <= 8.0f);
;                     float mn = mrow[mt], alpha = 1.f;
	v_mfma_f32_16x16x32_bf16 v[100:103], v[144:147], v[0:3], v[100:103]
	v_mfma_f32_16x16x32_bf16 v[116:119], v[144:147], v[16:19], v[116:119]
	v_mfma_f32_16x16x32_bf16 v[100:103], v[148:151], v[4:7], v[100:103]
	v_mfma_f32_16x16x32_bf16 v[116:119], v[148:151], v[20:23], v[116:119]
	v_mfma_f32_16x16x32_bf16 v[100:103], v[152:155], v[8:11], v[100:103]
	v_mfma_f32_16x16x32_bf16 v[116:119], v[152:155], v[24:27], v[116:119]
	v_mfma_f32_16x16x32_bf16 v[100:103], v[156:159], v[12:15], v[100:103]
	v_mfma_f32_16x16x32_bf16 v[116:119], v[156:159], v[28:31], v[116:119]
	s_waitcnt lgkmcnt(0)
	v_mfma_f32_16x16x32_bf16 v[120:123], v[202:205], v[16:19], v[120:123]
	v_mfma_f32_16x16x32_bf16 v[120:123], v[206:209], v[20:23], v[120:123]
	v_mfma_f32_16x16x32_bf16 v[120:123], v[210:213], v[24:27], v[120:123]
	v_mfma_f32_16x16x32_bf16 v[120:123], v[214:217], v[28:31], v[120:123]
	ds_read_b64 v[128:129], v182
	ds_read_b64 v[130:131], v183
	ds_read_b64 v[132:133], v182 offset:2048
	ds_read_b64 v[134:135], v183 offset:2048
	ds_read_b64 v[136:137], v182 offset:4096
	ds_read_b64 v[138:139], v183 offset:4096
	ds_read_b64 v[140:141], v182 offset:6144
	ds_read_b64 v[142:143], v183 offset:6144
	ds_read_b64 v[144:145], v182 offset:8192
	ds_read_b64 v[146:147], v183 offset:8192
	ds_read_b64 v[148:149], v182 offset:10240
	ds_read_b64 v[150:151], v183 offset:10240
	ds_read_b64 v[152:153], v182 offset:12288
	ds_read_b64 v[154:155], v183 offset:12288
	ds_read_b64 v[156:157], v182 offset:14336
	ds_read_b64 v[158:159], v183 offset:14336
	v_max3_f32 v232, v96, v97, v98
	v_max3_f32 v234, v99, v100, v101
	v_max_f32_e32 v236, v102, v103
	v_max3_f32 v232, v232, v234, v236
	v_max3_f32 v233, v112, v113, v114
	v_max3_f32 v235, v115, v116, v117
	v_max3_f32 v237, v118, v119, v120
	v_max3_f32 v233, v233, v121, v122
	v_max_f32_e32 v233, v233, v123
	v_max3_f32 v233, v233, v235, v237
	v_mul_f32_e32 v232, s30, v232
	v_mul_f32_e32 v233, s30, v233
	v_sub_f32_e32 v236, v232, v222
	v_sub_f32_e32 v237, v233, v223
	v_max_f32_e32 v236, v236, v237
	v_cmp_lt_f32_e32 vcc, 0x41000000, v236
	s_cbranch_vccz .Lna_fast_band0
	ds_bpermute_b32 v234, v218, v232
	ds_bpermute_b32 v235, v218, v233
	s_waitcnt lgkmcnt(0)
	v_max_f32_e32 v232, v232, v234
	v_max_f32_e32 v233, v233, v235
	ds_bpermute_b32 v234, v219, v232
	ds_bpermute_b32 v235, v219, v233
	s_waitcnt lgkmcnt(0)
	v_max_f32_e32 v232, v232, v234
	v_max_f32_e32 v233, v233, v235
	v_max_f32_e32 v236, v222, v232
	v_sub_f32_e32 v237, v222, v236
	v_exp_f32_e32 v237, v237
	v_mov_b32_e32 v222, v236
	v_sub_f32_e32 v226, 0, v236
	v_mul_f32_e32 v224, v224, v237
	v_mul_f32_e32 v32, v32, v237
	v_mul_f32_e32 v33, v33, v237
	v_mul_f32_e32 v34, v34, v237
	v_mul_f32_e32 v35, v35, v237
	v_mul_f32_e32 v36, v36, v237
	v_mul_f32_e32 v37, v37, v237
	v_mul_f32_e32 v38, v38, v237
	v_mul_f32_e32 v39, v39, v237
	v_mul_f32_e32 v40, v40, v237
	v_mul_f32_e32 v41, v41, v237
	v_mul_f32_e32 v42, v42, v237
	v_mul_f32_e32 v43, v43, v237
	v_mul_f32_e32 v44, v44, v237
	v_mul_f32_e32 v45, v45, v237
	v_mul_f32_e32 v46, v46, v237
	v_mul_f32_e32 v47, v47, v237
	v_mul_f32_e32 v48, v48, v237
	v_mul_f32_e32 v49, v49, v237
	v_mul_f32_e32 v50, v50, v237
	v_mul_f32_e32 v51, v51, v237
	v_mul_f32_e32 v52, v52, v237
	v_mul_f32_e32 v53, v53, v237
	v_mul_f32_e32 v54, v54, v237
	v_mul_f32_e32 v55, v55, v237
	v_mul_f32_e32 v56, v56, v237
	v_mul_f32_e32 v57, v57, v237
	v_mul_f32_e32 v58, v58, v237
	v_mul_f32_e32 v59, v59, v237
	v_mul_f32_e32 v60, v60, v237
	v_mul_f32_e32 v61, v61, v237
	v_mul_f32_e32 v62, v62, v237
	v_mul_f32_e32 v63, v63, v237
	v_max_f32_e32 v236, v223, v233
	v_sub_f32_e32 v237, v223, v236
	v_exp_f32_e32 v237, v237
	v_mov_b32_e32 v223, v236
	v_sub_f32_e32 v227, 0, v236
	v_mul_f32_e32 v225, v225, v237
	v_mul_f32_e32 v64, v64, v237
	v_mul_f32_e32 v65, v65, v237
	v_mul_f32_e32 v66, v66, v237
	v_mul_f32_e32 v67, v67, v237
	v_mul_f32_e32 v68, v68, v237
	v_mul_f32_e32 v69, v69, v237
	v_mul_f32_e32 v70, v70, v237
	v_mul_f32_e32 v71, v71, v237
	v_mul_f32_e32 v72, v72, v237
	v_mul_f32_e32 v73, v73, v237
	v_mul_f32_e32 v74, v74, v237
	v_mul_f32_e32 v75, v75, v237
	v_mul_f32_e32 v76, v76, v237
	v_mul_f32_e32 v77, v77, v237
	v_mul_f32_e32 v78, v78, v237
	v_mul_f32_e32 v79, v79, v237
	v_mul_f32_e32 v80, v80, v237
	v_mul_f32_e32 v81, v81, v237
	v_mul_f32_e32 v82, v82, v237
	v_mul_f32_e32 v83, v83, v237
	v_mul_f32_e32 v84, v84, v237
	v_mul_f32_e32 v85, v85, v237
	v_mul_f32_e32 v86, v86, v237
	v_mul_f32_e32 v87, v87, v237
	v_mul_f32_e32 v88, v88, v237
	v_mul_f32_e32 v89, v89, v237
	v_mul_f32_e32 v90, v90, v237
	v_mul_f32_e32 v91, v91, v237
	v_mul_f32_e32 v92, v92, v237
	v_mul_f32_e32 v93, v93, v237
	v_mul_f32_e32 v94, v94, v237
	v_mul_f32_e32 v95, v95, v237
; __device__ __forceinline__ void phase_na(const Params& p, unsigned char* lds) {
;     ...
;                     float ls = 0.f;
; #pragma unroll
;                     for (int nt = 0; nt < 4; ++nt) {
;                         const bool act = !band || (16 * nt < whi && 16 * nt + 16 > wlo);
;                         if (act) { const float p0 = __builtin_amdgcn_exp2f(st[mt][nt][0] - mn), p1 = __builtin_amdgcn_exp2f(st[mt][nt][1] - mn), p2 = __builtin_amdgcn_exp2f(st[mt][nt][2] - mn), p3 = __builtin_amdgcn_exp2f(st[mt][nt][3] - mn);
;                             ls += (p0 + p1) + (p2 + p3); pk[mt][nt][0] = pk2(p0, p1); pk[mt][nt][1] = pk2(p2, p3); }
;                         else { pk[mt][nt][0] = 0u; pk[mt][nt][1] = 0u; }
;                     }
;                     lrow[mt] = lrow[mt] * alpha + ls;
;                     if (resc) {
; #pragma unroll
;                         for (int dt = 0; dt < 8; ++dt) Oa[mt][dt] = Oa[mt][dt] * alpha; }
;                 }
;                 __builtin_amdgcn_sched_barrier(0);
; #pragma unroll
;                 for (int kk = 0; kk < 2; ++kk) {
;                     const int ta = 2 * kk, tb = 2 * kk + 1;
;                     const bf16x8 Bp0 = as_bf16x8((u32x4){pk[0][ta][0], pk[0][ta][1], pk[0][tb][0], pk[0][tb][1]}), Bp1 = as_bf16x8((u32x4){pk[1][ta][0], pk[1][ta][1], pk[1][tb][0], pk[1][tb][1]});
; #pragma unroll
;                     for (int dt = 0; dt < 8; ++dt) {
;                         const u32x2 va = *(const u32x2*)(vt + (dt * 16 + fr) * 72 + 16 * ta + fq * 4), vb = *(const u32x2*)(vt + (dt * 16 + fr) * 72 + 16 * tb + fq * 4);
;                         const bf16x8 Av = as_bf16x8((u32x4){va.x, va.y, vb.x, vb.y});
;                         Oa[0][dt] = __builtin_amdgcn_mfma_f32_16x16x32_bf16(Av, Bp0, Oa[0][dt], 0, 0, 0);
;                         Oa[1][dt] = __builtin_amdgcn_mfma_f32_16x16x32_bf16(Av, Bp1, Oa[1][dt], 0, 0, 0); }
;                     __builtin_amdgcn_sched_group_barrier(0x100, 8, 0);
; #pragma unroll
;                     for (int q = 0; q < 4; ++q) { __builtin_amdgcn_sched_group_barrier(0x008, 2, 0); __builtin_amdgcn_sched_group_barrier(0x100, 2, 0); }
;                     __builtin_amdgcn_sched_group_barrier(0x008, 8, 0);
;                     __builtin_amdgcn_sched_barrier(0);
;                 }
.Lna_fast_band0:
	v_fma_f32 v96, v96, s30, v226
	v_fma_f32 v97, v97, s30, v226
	v_fma_f32 v98, v98, s30, v226
	v_fma_f32 v99, v99, s30, v226
	v_fma_f32 v100, v100, s30, v226
	v_fma_f32 v101, v101, s30, v226
	v_fma_f32 v102, v102, s30, v226
	v_fma_f32 v103, v103, s30, v226
	v_fma_f32 v112, v112, s30, v227
	v_fma_f32 v113, v113, s30, v227
	v_fma_f32 v114, v114, s30, v227
	v_fma_f32 v115, v115, s30, v227
	v_fma_f32 v116, v116, s30, v227
	v_fma_f32 v117, v117, s30, v227
	v_fma_f32 v118, v118, s30, v227
	v_fma_f32 v119, v119, s30, v227
	v_fma_f32 v120, v120, s30, v227
	v_fma_f32 v121, v121, s30, v227
	v_fma_f32 v122, v122, s30, v227
	v_fma_f32 v123, v123, s30, v227
	v_exp_f32_e32 v96, v96
	v_exp_f32_e32 v97, v97
	v_exp_f32_e32 v98, v98
	v_exp_f32_e32 v99, v99
	v_exp_f32_e32 v100, v100
	v_exp_f32_e32 v101, v101
	v_exp_f32_e32 v102, v102
	v_exp_f32_e32 v103, v103
	v_exp_f32_e32 v112, v112
	v_exp_f32_e32 v113, v113
	v_exp_f32_e32 v114, v114
	v_exp_f32_e32 v115, v115
	v_exp_f32_e32 v116, v116
	v_exp_f32_e32 v117, v117
	v_exp_f32_e32 v118, v118
	v_exp_f32_e32 v119, v119
	v_exp_f32_e32 v120, v120
	v_exp_f32_e32 v121, v121
	v_exp_f32_e32 v122, v122
	v_exp_f32_e32 v123, v123
	v_add_f32_e32 v232, v96, v97
	v_add_f32_e32 v232, v232, v98
	v_add_f32_e32 v232, v232, v99
	v_add_f32_e32 v232, v232, v100
	v_add_f32_e32 v232, v232, v101
	v_add_f32_e32 v232, v232, v102
	v_add_f32_e32 v232, v232, v103
	v_add_f32_e32 v224, v224, v232
	v_add_f32_e32 v233, v112, v113
	v_add_f32_e32 v233, v233, v114
	v_add_f32_e32 v233, v233, v115
	v_add_f32_e32 v233, v233, v116
	v_add_f32_e32 v233, v233, v117
	v_add_f32_e32 v233, v233, v118
	v_add_f32_e32 v233, v233, v119
	v_add_f32_e32 v233, v233, v120
	v_add_f32_e32 v233, v233, v121
	v_add_f32_e32 v233, v233, v122
	v_add_f32_e32 v233, v233, v123
	v_add_f32_e32 v225, v225, v233
	v_cvt_pk_bf16_f32 v96, v96, v97
	v_cvt_pk_bf16_f32 v97, v98, v99
	v_cvt_pk_bf16_f32 v98, v100, v101
	v_cvt_pk_bf16_f32 v99, v102, v103
	v_cvt_pk_bf16_f32 v112, v112, v113
	v_cvt_pk_bf16_f32 v113, v114, v115
	v_cvt_pk_bf16_f32 v114, v116, v117
	v_cvt_pk_bf16_f32 v115, v118, v119
	v_cvt_pk_bf16_f32 v120, v120, v121
	v_cvt_pk_bf16_f32 v121, v122, v123
	v_mov_b32_e32 v122, 0
	v_mov_b32_e32 v123, 0
	s_waitcnt lgkmcnt(0)
	s_nop 1
	v_mfma_f32_16x16x32_bf16 v[32:35], v[128:131], v[96:99], v[32:35]
	v_mfma_f32_16x16x32_bf16 v[64:67], v[128:131], v[112:115], v[64:67]
	v_mfma_f32_16x16x32_bf16 v[36:39], v[132:135], v[96:99], v[36:39]
	v_mfma_f32_16x16x32_bf16 v[68:71], v[132:135], v[112:115], v[68:71]
	v_mfma_f32_16x16x32_bf16 v[40:43], v[136:139], v[96:99], v[40:43]
	v_mfma_f32_16x16x32_bf16 v[72:75], v[136:139], v[112:115], v[72:75]
	v_mfma_f32_16x16x32_bf16 v[44:47], v[140:143], v[96:99], v[44:47]
	v_mfma_f32_16x16x32_bf16 v[76:79], v[140:143], v[112:115], v[76:79]
	ds_read_b64 v[128:129], v184
	ds_read_b64 v[130:131], v185
	ds_read_b64 v[132:133], v184 offset:2048
	ds_read_b64 v[134:135], v185 offset:2048
	ds_read_b64 v[136:137], v184 offset:4096
	ds_read_b64 v[138:139], v185 offset:4096
	ds_read_b64 v[140:141], v184 offset:6144
	ds_read_b64 v[142:143], v185 offset:6144
	v_mfma_f32_16x16x32_bf16 v[48:51], v[144:147], v[96:99], v[48:51]
	v_mfma_f32_16x16x32_bf16 v[80:83], v[144:147], v[112:115], v[80:83]
	v_mfma_f32_16x16x32_bf16 v[52:55], v[148:151], v[96:99], v[52:55]
	v_mfma_f32_16x16x32_bf16 v[84:87], v[148:151], v[112:115], v[84:87]
	v_mfma_f32_16x16x32_bf16 v[56:59], v[152:155], v[96:99], v[56:59]
	v_mfma_f32_16x16x32_bf16 v[88:91], v[152:155], v[112:115], v[88:91]
	v_mfma_f32_16x16x32_bf16 v[60:63], v[156:159], v[96:99], v[60:63]
	v_mfma_f32_16x16x32_bf16 v[92:95], v[156:159], v[112:115], v[92:95]
	ds_read_b64 v[144:145], v184 offset:8192
	ds_read_b64 v[146:147], v185 offset:8192
	ds_read_b64 v[148:149], v184 offset:10240
	ds_read_b64 v[150:151], v185 offset:10240
	ds_read_b64 v[152:153], v184 offset:12288
	ds_read_b64 v[154:155], v185 offset:12288
	ds_read_b64 v[156:157], v184 offset:14336
	ds_read_b64 v[158:159], v185 offset:14336
	s_waitcnt lgkmcnt(8)
	v_mfma_f32_16x16x32_bf16 v[64:67], v[128:131], v[120:123], v[64:67]
	v_mfma_f32_16x16x32_bf16 v[68:71], v[132:135], v[120:123], v[68:71]
	v_mfma_f32_16x16x32_bf16 v[72:75], v[136:139], v[120:123], v[72:75]
	v_mfma_f32_16x16x32_bf16 v[76:79], v[140:143], v[120:123], v[76:79]
	s_waitcnt lgkmcnt(0)
	v_mfma_f32_16x16x32_bf16 v[80:83], v[144:147], v[120:123], v[80:83]
	v_mfma_f32_16x16x32_bf16 v[84:87], v[148:151], v[120:123], v[84:87]
	v_mfma_f32_16x16x32_bf16 v[88:91], v[152:155], v[120:123], v[88:91]
	v_mfma_f32_16x16x32_bf16 v[92:95], v[156:159], v[120:123], v[92:95]
	s_branch .Lna_after
; __device__ __forceinline__ void phase_na(const Params& p, unsigned char* lds) {
;     ...
;             const bool band = kt >= 4; const int kr = rs_lo + kt - 4;
;             if (!(band && (kr < rsq || kr >= rsq + 8))) {
;                 const bf16_t* Kt = KtB + (kt & 1) * (64 * 136); const bf16_t* vt = vtB + (kt & 1) * (128 * 72);
;                 f32x4 st[2][4];
;                 const int wlo0 = min(max(qc0 - 8, 0), 48), whi0 = min(max(qc0 + 7, 0), 48) + 16, wlo1 = min(max(qc0 + 8, 0), 48), whi1 = min(max(qc0 + 23, 0), 48) + 16;
; #pragma unroll
;                 for (int nt = 0; nt < 4; ++nt) {
;                     const bool act0 = !band || (16 * nt < whi0 && 16 * nt + 16 > wlo0), act1 = !band || (16 * nt < whi1 && 16 * nt + 16 > wlo1);
;                     st[0][nt] = (f32x4){0.f, 0.f, 0.f, 0.f}; st[1][nt] = (f32x4){0.f, 0.f, 0.f, 0.f};
;                     if (act0 || act1) {
;                         bf16x8 Bk[4];
; #pragma unroll
;                         for (int ks = 0; ks < 4; ++ks) Bk[ks] = *(const bf16x8*)(Kt + (nt * 16 + fr) * 136 + ks * 32 + fq * 8);
; #pragma unroll
;                         for (int ks = 0; ks < 4; ++ks) {
;                             if (act0) st[0][nt] = __builtin_amdgcn_mfma_f32_16x16x32_bf16(Bk[ks], aq[0][ks], st[0][nt], 0, 0, 0);
;                             if (act1) st[1][nt] = __builtin_amdgcn_mfma_f32_16x16x32_bf16(Bk[ks], aq[1][ks], st[1][nt], 0, 0, 0); }
;                     }
;                 }
;                 unsigned pk[2][4][2];
; #pragma unroll
;                 for (int mt = 0; mt < 2; ++mt) {
;                     __builtin_amdgcn_sched_barrier(0);
;                     const int c = qc0 + 16 * mt + fr; const int cs = min(max(c - 8, 0), 48); const int wlo = mt ? wlo1 : wlo0, whi = mt ? whi1 : whi0;
;                     float mx = -1e30f;
; #pragma unroll
;                     for (int nt = 0; nt < 4; ++nt) {
;                         const bool act = !band || (16 * nt < whi && 16 * nt + 16 > wlo);
;                         if (act) {
; #pragma unroll
;                             for (int j = 0; j < 4; ++j) { float v = st[mt][nt][j] * scale;
;                                 if (band) { const int kc = nt * 16 + fq * 4 + j; const bool valid = kc >= cs && kc < cs + 16; const int dci = min(max(kc - c + 15, 0), 30);
.Lna_c_band1:
	v_add_u32_e32 v230, s22, v220
	v_add_u32_e32 v231, s22, v221
	ds_read2_b32 v[100:101], v230 offset0:16 offset1:17
	ds_read2_b32 v[102:103], v230 offset0:18 offset1:19
	ds_read2_b32 v[104:105], v230 offset0:32 offset1:33
	ds_read2_b32 v[106:107], v230 offset0:34 offset1:35
	ds_read2_b32 v[108:109], v230 offset0:48 offset1:49
	ds_read2_b32 v[110:111], v230 offset0:50 offset1:51
	ds_read2_b32 v[120:121], v231 offset0:32 offset1:33
	ds_read2_b32 v[122:123], v231 offset0:34 offset1:35
	ds_read2_b32 v[124:125], v231 offset0:48 offset1:49
	ds_read2_b32 v[126:127], v231 offset0:50 offset1:51
	ds_read_b128 v[128:131], v178 offset:4096
	ds_read_b128 v[132:135], v179 offset:4096
	ds_read_b128 v[136:139], v180 offset:4096
	ds_read_b128 v[140:143], v181 offset:4096
	ds_read_b128 v[144:147], v178 offset:8192
	ds_read_b128 v[148:151], v179 offset:8192
	ds_read_b128 v[152:155], v180 offset:8192
	ds_read_b128 v[156:159], v181 offset:8192
	s_waitcnt lgkmcnt(8)
	v_mov_b32_e32 v232, 0xf149f2ca
	v_add_f32_e32 v100, v100, v190
	v_add_f32_e32 v101, v101, v191
	v_add_f32_e32 v102, v102, v192
	v_add_f32_e32 v103, v103, v193
	v_add_f32_e32 v104, v104, v194
	v_add_f32_e32 v105, v105, v195
	v_add_f32_e32 v106, v106, v196
	v_add_f32_e32 v107, v107, v197
	v_add_f32_e32 v108, v108, v198
	v_add_f32_e32 v109, v109, v199
	v_add_f32_e32 v110, v110, v200
	v_add_f32_e32 v111, v111, v201
	v_cndmask_b32_e64 v120, v232, v120, s[48:49]
	v_cndmask_b32_e64 v121, v232, v121, s[50:51]
	v_cndmask_b32_e64 v122, v232, v122, s[52:53]
	v_cndmask_b32_e64 v123, v232, v123, s[54:55]
	v_cndmask_b32_e64 v124, v232, v124, s[56:57]
	v_cndmask_b32_e64 v125, v232, v125, s[58:59]
	v_cndmask_b32_e64 v126, v232, v126, s[60:61]
	v_cndmask_b32_e64 v127, v232, v127, s[62:63]
	ds_read_b128 v[202:205], v178 offset:12288
	ds_read_b128 v[206:209], v179 offset:12288
	ds_read_b128 v[210:213], v180 offset:12288
	ds_read_b128 v[214:217], v181 offset:12288
	s_waitcnt lgkmcnt(8)
	v_mfma_f32_16x16x32_bf16 v[100:103], v[128:131], v[0:3], v[100:103]
	v_mfma_f32_16x16x32_bf16 v[100:103], v[132:135], v[4:7], v[100:103]
	v_mfma_f32_16x16x32_bf16 v[100:103], v[136:139], v[8:11], v[100:103]
	v_mfma_f32_16x16x32_bf16 v[100:103], v[140:143], v[12:15], v[100:103]
	s_waitcnt lgkmcnt(4)
	v_mfma_f32_16x16x32_bf16 v[104:107], v[144:147], v[0:3], v[104:107]
	v_mfma_f32_16x16x32_bf16 v[120:123], v[144:147], v[16:19], v[120:123]
	v_mfma_f32_16x16x32_bf16 v[104:107], v[148:151], v[4:7], v[104:107]
	v_mfma_f32_16x16x32_bf16 v[120:123], v[148:151], v[20:23], v[120:123]
	v_mfma_f32_16x16x32_bf16 v[104:107], v[152:155], v[8:11], v[104:107]
	v_mfma_f32_16x16x32_bf16 v[120:123], v[152:155], v[24:27], v[120:123]
	v_mfma_f32_16x16x32_bf16 v[104:107], v[156:159], v[12:15], v[104:107]
	v_mfma_f32_16x16x32_bf16 v[120:123], v[156:159], v[28:31], v[120:123]
	s_waitcnt lgkmcnt(0)
	v_mfma_f32_16x16x32_bf16 v[108:111], v[202:205], v[0:3], v[108:111]
	v_mfma_f32_16x16x32_bf16 v[124:127], v[202:205], v[16:19], v[124:127]
	v_mfma_f32_16x16x32_bf16 v[108:111], v[206:209], v[4:7], v[108:111]
	v_mfma_f32_16x16x32_bf16 v[124:127], v[206:209], v[20:23], v[124:127]
	v_mfma_f32_16x16x32_bf16 v[108:111], v[210:213], v[8:11], v[108:111]
	v_mfma_f32_16x16x32_bf16 v[124:127], v[210:213], v[24:27], v[124:127]
	v_mfma_f32_16x16x32_bf16 v[108:111], v[214:217], v[12:15], v[108:111]
	v_mfma_f32_16x16x32_bf16 v[124:127], v[214:217], v[28:31], v[124:127]
	ds_read_b64 v[128:129], v182
	ds_read_b64 v[130:131], v183
	ds_read_b64 v[132:133], v182 offset:2048
	ds_read_b64 v[134:135], v183 offset:2048
	ds_read_b64 v[136:137], v182 offset:4096
	ds_read_b64 v[138:139], v183 offset:4096
	ds_read_b64 v[140:141], v182 offset:6144
	ds_read_b64 v[142:143], v183 offset:6144
	ds_read_b64 v[144:145], v182 offset:8192
	ds_read_b64 v[146:147], v183 offset:8192
	ds_read_b64 v[148:149], v182 offset:10240
	ds_read_b64 v[150:151], v183 offset:10240
	ds_read_b64 v[152:153], v182 offset:12288
	ds_read_b64 v[154:155], v183 offset:12288
	ds_read_b64 v[156:157], v182 offset:14336
	ds_read_b64 v[158:159], v183 offset:14336
	v_max3_f32 v232, v100, v101, v102
	v_max3_f32 v234, v103, v104, v105
	v_max3_f32 v236, v106, v107, v108
	v_max3_f32 v232, v232, v109, v110
	v_max_f32_e32 v232, v232, v111
	v_max3_f32 v232, v232, v234, v236
	v_max3_f32 v233, v120, v121, v122
	v_max3_f32 v235, v123, v124, v125
	v_max_f32_e32 v237, v126, v127
	v_max3_f32 v233, v233, v235, v237
	v_mul_f32_e32 v232, s30, v232
	v_mul_f32_e32 v233, s30, v233
	v_sub_f32_e32 v236, v232, v222
	v_sub_f32_e32 v237, v233, v223
	v_max_f32_e32 v236, v236, v237
	v_cmp_lt_f32_e32 vcc, 0x41000000, v236
	s_cbranch_vccz .Lna_fast_band1
; __device__ __forceinline__ void phase_na(const Params& p, unsigned char* lds) {
;     ...
;                     mx = fmaxf(mx, __shfl_xor(mx, 16)); mx = fmaxf(mx, __shfl_xor(mx, 32));
;                     const bool resc = !__all(mx - mrow[mt] <= 8.0f);
;                     float mn = mrow[mt], alpha = 1.f;
;                     if (resc) { mn = fmaxf(mrow[mt], mx); alpha = __builtin_amdgcn_exp2f(mrow[mt] - mn); mrow[mt] = mn; }
;                     float ls = 0.f;
; #pragma unroll
;                     for (int nt = 0; nt < 4; ++nt) {
;                         const bool act = !band || (16 * nt < whi && 16 * nt + 16 > wlo);
;                         if (act) { const float p0 = __builtin_amdgcn_exp2f(st[mt][nt][0] - mn), p1 = __builtin_amdgcn_exp2f(st[mt][nt][1] - mn), p2 = __builtin_amdgcn_exp2f(st[mt][nt][2] - mn), p3 = __builtin_amdgcn_exp2f(st[mt][nt][3] - mn);
;                             ls += (p0 + p1) + (p2 + p3); pk[mt][nt][0] = pk2(p0, p1); pk[mt][nt][1] = pk2(p2, p3); }
;                         else { pk[mt][nt][0] = 0u; pk[mt][nt][1] = 0u; }
;                     }
;                     lrow[mt] = lrow[mt] * alpha + ls;
;                     if (resc) {
; #pragma unroll
;                         for (int dt = 0; dt < 8; ++dt) Oa[mt][dt] = Oa[mt][dt] * alpha; }
;                 }
;                 __builtin_amdgcn_sched_barrier(0);
; #pragma unroll
;                 for (int kk = 0; kk < 2; ++kk) {
;                     const int ta = 2 * kk, tb = 2 * kk + 1;
;                     const bf16x8 Bp0 = as_bf16x8((u32x4){pk[0][ta][0], pk[0][ta][1], pk[0][tb][0], pk[0][tb][1]}), Bp1 = as_bf16x8((u32x4){pk[1][ta][0], pk[1][ta][1], pk[1][tb][0], pk[1][tb][1]});
; #pragma unroll
;                     for (int dt = 0; dt < 8; ++dt) {
;                         const u32x2 va = *(const u32x2*)(vt + (dt * 16 + fr) * 72 + 16 * ta + fq * 4), vb = *(const u32x2*)(vt + (dt * 16 + fr) * 72 + 16 * tb + fq * 4);
;                         const bf16x8 Av = as_bf16x8((u32x4){va.x, va.y, vb.x, vb.y});
;                         Oa[0][dt] = __builtin_amdgcn_mfma_f32_16x16x32_bf16(Av, Bp0, Oa[0][dt], 0, 0, 0);
;                         Oa[1][dt] = __builtin_amdgcn_mfma_f32_16x16x32_bf16(Av, Bp1, Oa[1][dt], 0, 0, 0); }
;                     __builtin_amdgcn_sched_group_barrier(0x100, 8, 0);
; #pragma unroll
	ds_bpermute_b32 v234, v218, v232
	ds_bpermute_b32 v235, v218, v233
	s_waitcnt lgkmcnt(0)
	v_max_f32_e32 v232, v232, v234
	v_max_f32_e32 v233, v233, v235
	ds_bpermute_b32 v234, v219, v232
	ds_bpermute_b32 v235, v219, v233
	s_waitcnt lgkmcnt(0)
	v_max_f32_e32 v232, v232, v234
	v_max_f32_e32 v233, v233, v235
	v_max_f32_e32 v236, v222, v232
	v_sub_f32_e32 v237, v222, v236
	v_exp_f32_e32 v237, v237
	v_mov_b32_e32 v222, v236
	v_sub_f32_e32 v226, 0, v236
	v_mul_f32_e32 v224, v224, v237
	v_mul_f32_e32 v32, v32, v237
	v_mul_f32_e32 v33, v33, v237
	v_mul_f32_e32 v34, v34, v237
	v_mul_f32_e32 v35, v35, v237
	v_mul_f32_e32 v36, v36, v237
	v_mul_f32_e32 v37, v37, v237
	v_mul_f32_e32 v38, v38, v237
	v_mul_f32_e32 v39, v39, v237
	v_mul_f32_e32 v40, v40, v237
	v_mul_f32_e32 v41, v41, v237
	v_mul_f32_e32 v42, v42, v237
	v_mul_f32_e32 v43, v43, v237
	v_mul_f32_e32 v44, v44, v237
	v_mul_f32_e32 v45, v45, v237
	v_mul_f32_e32 v46, v46, v237
	v_mul_f32_e32 v47, v47, v237
	v_mul_f32_e32 v48, v48, v237
	v_mul_f32_e32 v49, v49, v237
	v_mul_f32_e32 v50, v50, v237
	v_mul_f32_e32 v51, v51, v237
	v_mul_f32_e32 v52, v52, v237
	v_mul_f32_e32 v53, v53, v237
	v_mul_f32_e32 v54, v54, v237
	v_mul_f32_e32 v55, v55, v237
	v_mul_f32_e32 v56, v56, v237
	v_mul_f32_e32 v57, v57, v237
	v_mul_f32_e32 v58, v58, v237
	v_mul_f32_e32 v59, v59, v237
	v_mul_f32_e32 v60, v60, v237
	v_mul_f32_e32 v61, v61, v237
	v_mul_f32_e32 v62, v62, v237
	v_mul_f32_e32 v63, v63, v237
	v_max_f32_e32 v236, v223, v233
	v_sub_f32_e32 v237, v223, v236
	v_exp_f32_e32 v237, v237
	v_mov_b32_e32 v223, v236
	v_sub_f32_e32 v227, 0, v236
	v_mul_f32_e32 v225, v225, v237
	v_mul_f32_e32 v64, v64, v237
	v_mul_f32_e32 v65, v65, v237
	v_mul_f32_e32 v66, v66, v237
	v_mul_f32_e32 v67, v67, v237
	v_mul_f32_e32 v68, v68, v237
	v_mul_f32_e32 v69, v69, v237
	v_mul_f32_e32 v70, v70, v237
	v_mul_f32_e32 v71, v71, v237
	v_mul_f32_e32 v72, v72, v237
	v_mul_f32_e32 v73, v73, v237
	v_mul_f32_e32 v74, v74, v237
	v_mul_f32_e32 v75, v75, v237
	v_mul_f32_e32 v76, v76, v237
	v_mul_f32_e32 v77, v77, v237
	v_mul_f32_e32 v78, v78, v237
	v_mul_f32_e32 v79, v79, v237
	v_mul_f32_e32 v80, v80, v237
	v_mul_f32_e32 v81, v81, v237
	v_mul_f32_e32 v82, v82, v237
	v_mul_f32_e32 v83, v83, v237
	v_mul_f32_e32 v84, v84, v237
	v_mul_f32_e32 v85, v85, v237
	v_mul_f32_e32 v86, v86, v237
	v_mul_f32_e32 v87, v87, v237
	v_mul_f32_e32 v88, v88, v237
	v_mul_f32_e32 v89, v89, v237
	v_mul_f32_e32 v90, v90, v237
	v_mul_f32_e32 v91, v91, v237
	v_mul_f32_e32 v92, v92, v237
	v_mul_f32_e32 v93, v93, v237
	v_mul_f32_e32 v94, v94, v237
	v_mul_f32_e32 v95, v95, v237
.Lna_fast_band1:
	v_fma_f32 v100, v100, s30, v226
	v_fma_f32 v101, v101, s30, v226
	v_fma_f32 v102, v102, s30, v226
	v_fma_f32 v103, v103, s30, v226
	v_fma_f32 v104, v104, s30, v226
	v_fma_f32 v105, v105, s30, v226
	v_fma_f32 v106, v106, s30, v226
	v_fma_f32 v107, v107, s30, v226
	v_fma_f32 v108, v108, s30, v226
	v_fma_f32 v109, v109, s30, v226
	v_fma_f32 v110, v110, s30, v226
	v_fma_f32 v111, v111, s30, v226
	v_fma_f32 v120, v120, s30, v227
	v_fma_f32 v121, v121, s30, v227
	v_fma_f32 v122, v122, s30, v227
	v_fma_f32 v123, v123, s30, v227
	v_fma_f32 v124, v124, s30, v227
	v_fma_f32 v125, v125, s30, v227
	v_fma_f32 v126, v126, s30, v227
	v_fma_f32 v127, v127, s30, v227
	v_exp_f32_e32 v100, v100
	v_exp_f32_e32 v101, v101
	v_exp_f32_e32 v102, v102
	v_exp_f32_e32 v103, v103
	v_exp_f32_e32 v104, v104
	v_exp_f32_e32 v105, v105
	v_exp_f32_e32 v106, v106
	v_exp_f32_e32 v107, v107
	v_exp_f32_e32 v108, v108
	v_exp_f32_e32 v109, v109
	v_exp_f32_e32 v110, v110
	v_exp_f32_e32 v111, v111
	v_exp_f32_e32 v120, v120
	v_exp_f32_e32 v121, v121
	v_exp_f32_e32 v122, v122
	v_exp_f32_e32 v123, v123
	v_exp_f32_e32 v124, v124
	v_exp_f32_e32 v125, v125
	v_exp_f32_e32 v126, v126
	v_exp_f32_e32 v127, v127
	v_add_f32_e32 v232, v100, v101
	v_add_f32_e32 v232, v232, v102
	v_add_f32_e32 v232, v232, v103
	v_add_f32_e32 v232, v232, v104
	v_add_f32_e32 v232, v232, v105
	v_add_f32_e32 v232, v232, v106
	v_add_f32_e32 v232, v232, v107
	v_add_f32_e32 v232, v232, v108
	v_add_f32_e32 v232, v232, v109
	v_add_f32_e32 v232, v232, v110
	v_add_f32_e32 v232, v232, v111
	v_add_f32_e32 v224, v224, v232
	v_add_f32_e32 v233, v120, v121
	v_add_f32_e32 v233, v233, v122
	v_add_f32_e32 v233, v233, v123
	v_add_f32_e32 v233, v233, v124
	v_add_f32_e32 v233, v233, v125
	v_add_f32_e32 v233, v233, v126
	v_add_f32_e32 v233, v233, v127
	v_add_f32_e32 v225, v225, v233
	v_mov_b32_e32 v96, 0
	v_mov_b32_e32 v97, 0
	v_cvt_pk_bf16_f32 v98, v100, v101
	v_cvt_pk_bf16_f32 v99, v102, v103
	v_cvt_pk_bf16_f32 v104, v104, v105
	v_cvt_pk_bf16_f32 v105, v106, v107
	v_cvt_pk_bf16_f32 v106, v108, v109
	v_cvt_pk_bf16_f32 v107, v110, v111
	v_cvt_pk_bf16_f32 v120, v120, v121
	v_cvt_pk_bf16_f32 v121, v122, v123
	v_cvt_pk_bf16_f32 v122, v124, v125
	v_cvt_pk_bf16_f32 v123, v126, v127
	s_waitcnt lgkmcnt(0)
	s_nop 1
	v_mfma_f32_16x16x32_bf16 v[32:35], v[128:131], v[96:99], v[32:35]
	v_mfma_f32_16x16x32_bf16 v[36:39], v[132:135], v[96:99], v[36:39]
	v_mfma_f32_16x16x32_bf16 v[40:43], v[136:139], v[96:99], v[40:43]
	v_mfma_f32_16x16x32_bf16 v[44:47], v[140:143], v[96:99], v[44:47]
	ds_read_b64 v[128:129], v184
	ds_read_b64 v[130:131], v185
	ds_read_b64 v[132:133], v184 offset:2048
	ds_read_b64 v[134:135], v185 offset:2048
	ds_read_b64 v[136:137], v184 offset:4096
	ds_read_b64 v[138:139], v185 offset:4096
	ds_read_b64 v[140:141], v184 offset:6144
	ds_read_b64 v[142:143], v185 offset:6144
	v_mfma_f32_16x16x32_bf16 v[48:51], v[144:147], v[96:99], v[48:51]
	v_mfma_f32_16x16x32_bf16 v[52:55], v[148:151], v[96:99], v[52:55]
	v_mfma_f32_16x16x32_bf16 v[56:59], v[152:155], v[96:99], v[56:59]
	v_mfma_f32_16x16x32_bf16 v[60:63], v[156:159], v[96:99], v[60:63]
	ds_read_b64 v[144:145], v184 offset:8192
	ds_read_b64 v[146:147], v185 offset:8192
	ds_read_b64 v[148:149], v184 offset:10240
	ds_read_b64 v[150:151], v185 offset:10240
	ds_read_b64 v[152:153], v184 offset:12288
	ds_read_b64 v[154:155], v185 offset:12288
	ds_read_b64 v[156:157], v184 offset:14336
	ds_read_b64 v[158:159], v185 offset:14336
	s_waitcnt lgkmcnt(8)
; __device__ __forceinline__ void phase_na(const Params& p, unsigned char* lds) {
;     ...
;                 for (int nt = 0; nt < 4; ++nt) {
;                     const bool act0 = !band || (16 * nt < whi0 && 16 * nt + 16 > wlo0), act1 = !band || (16 * nt < whi1 && 16 * nt + 16 > wlo1);
;                     st[0][nt] = (f32x4){0.f, 0.f, 0.f, 0.f}; st[1][nt] = (f32x4){0.f, 0.f, 0.f, 0.f};
;                     if (act0 || act1) {
;                         bf16x8 Bk[4];
; #pragma unroll
;                         for (int ks = 0; ks < 4; ++ks) Bk[ks] = *(const bf16x8*)(Kt + (nt * 16 + fr) * 136 + ks * 32 + fq * 8);
; #pragma unroll
;                         for (int ks = 0; ks < 4; ++ks) {
;                             if (act0) st[0][nt] = __builtin_amdgcn_mfma_f32_16x16x32_bf16(Bk[ks], aq[0][ks], st[0][nt], 0, 0, 0);
;                             if (act1) st[1][nt] = __builtin_amdgcn_mfma_f32_16x16x32_bf16(Bk[ks], aq[1][ks], st[1][nt], 0, 0, 0); }
;                     }
;                 }
;                 unsigned pk[2][4][2];
; #pragma unroll
;                 for (int mt = 0; mt < 2; ++mt) {
;                     __builtin_amdgcn_sched_barrier(0);
;                     const int c = qc0 + 16 * mt + fr; const int cs = min(max(c - 8, 0), 48); const int wlo = mt ? wlo1 : wlo0, whi = mt ? whi1 : whi0;
;                     float mx = -1e30f;
; #pragma unroll
;                     for (int nt = 0; nt < 4; ++nt) {
;                         const bool act = !band || (16 * nt < whi && 16 * nt + 16 > wlo);
;                         if (act) {
; #pragma unroll
;                             for (int j = 0; j < 4; ++j) { float v = st[mt][nt][j] * scale;
;                                 if (band) { const int kc = nt * 16 + fq * 4 + j; const bool valid = kc >= cs && kc < cs + 16; const int dci = min(max(kc - c + 15, 0), 30);
;                                     v += rbt[(kr - qr + 7) * 31 + dci]; v = valid ? v : -1e30f; }
;                                 st[mt][nt][j] = v; mx = fmaxf(mx, v); }
;                         }
;                     }
;                     mx = fmaxf(mx, __shfl_xor(mx, 16)); mx = fmaxf(mx, __shfl_xor(mx, 32));
;                     const bool resc = !__all(mx - mrow[mt] <= 8.0f);
;     ...
;                 __builtin_amdgcn_sched_barrier(0);
; #pragma unroll
;                 for (int kk = 0; kk < 2; ++kk) {
	v_mfma_f32_16x16x32_bf16 v[32:35], v[128:131], v[104:107], v[32:35]
	v_mfma_f32_16x16x32_bf16 v[64:67], v[128:131], v[120:123], v[64:67]
	v_mfma_f32_16x16x32_bf16 v[36:39], v[132:135], v[104:107], v[36:39]
	v_mfma_f32_16x16x32_bf16 v[68:71], v[132:135], v[120:123], v[68:71]
	v_mfma_f32_16x16x32_bf16 v[40:43], v[136:139], v[104:107], v[40:43]
	v_mfma_f32_16x16x32_bf16 v[72:75], v[136:139], v[120:123], v[72:75]
	v_mfma_f32_16x16x32_bf16 v[44:47], v[140:143], v[104:107], v[44:47]
	v_mfma_f32_16x16x32_bf16 v[76:79], v[140:143], v[120:123], v[76:79]
	s_waitcnt lgkmcnt(0)
	v_mfma_f32_16x16x32_bf16 v[48:51], v[144:147], v[104:107], v[48:51]
	v_mfma_f32_16x16x32_bf16 v[80:83], v[144:147], v[120:123], v[80:83]
	v_mfma_f32_16x16x32_bf16 v[52:55], v[148:151], v[104:107], v[52:55]
	v_mfma_f32_16x16x32_bf16 v[84:87], v[148:151], v[120:123], v[84:87]
	v_mfma_f32_16x16x32_bf16 v[56:59], v[152:155], v[104:107], v[56:59]
	v_mfma_f32_16x16x32_bf16 v[88:91], v[152:155], v[120:123], v[88:91]
	v_mfma_f32_16x16x32_bf16 v[60:63], v[156:159], v[104:107], v[60:63]
	v_mfma_f32_16x16x32_bf16 v[92:95], v[156:159], v[120:123], v[92:95]
	s_branch .Lna_after
.Lna_c_ctx:
	ds_read_b128 v[128:131], v178
	ds_read_b128 v[132:135], v179
	ds_read_b128 v[136:139], v180
	ds_read_b128 v[140:143], v181
	ds_read_b128 v[144:147], v178 offset:4096
	ds_read_b128 v[148:151], v179 offset:4096
	ds_read_b128 v[152:155], v180 offset:4096
	ds_read_b128 v[156:159], v181 offset:4096
	v_mov_b32_e32 v96, 0
	v_mov_b32_e32 v97, 0
	v_mov_b32_e32 v98, 0
	v_mov_b32_e32 v99, 0
	v_mov_b32_e32 v100, 0
	v_mov_b32_e32 v101, 0
	v_mov_b32_e32 v102, 0
	v_mov_b32_e32 v103, 0
	v_mov_b32_e32 v104, 0
	v_mov_b32_e32 v105, 0
	v_mov_b32_e32 v106, 0
	v_mov_b32_e32 v107, 0
	v_mov_b32_e32 v108, 0
	v_mov_b32_e32 v109, 0
	v_mov_b32_e32 v110, 0
	v_mov_b32_e32 v111, 0
	v_mov_b32_e32 v112, 0
	v_mov_b32_e32 v113, 0
	v_mov_b32_e32 v114, 0
	v_mov_b32_e32 v115, 0
	v_mov_b32_e32 v116, 0
	v_mov_b32_e32 v117, 0
	v_mov_b32_e32 v118, 0
	v_mov_b32_e32 v119, 0
	v_mov_b32_e32 v120, 0
	v_mov_b32_e32 v121, 0
	v_mov_b32_e32 v122, 0
	v_mov_b32_e32 v123, 0
	v_mov_b32_e32 v124, 0
	v_mov_b32_e32 v125, 0
	v_mov_b32_e32 v126, 0
	v_mov_b32_e32 v127, 0
	ds_read_b128 v[202:205], v178 offset:8192
	ds_read_b128 v[206:209], v179 offset:8192
	ds_read_b128 v[210:213], v180 offset:8192
	ds_read_b128 v[214:217], v181 offset:8192
	s_waitcnt lgkmcnt(8)
	v_mfma_f32_16x16x32_bf16 v[96:99], v[128:131], v[0:3], v[96:99]
	v_mfma_f32_16x16x32_bf16 v[112:115], v[128:131], v[16:19], v[112:115]
	v_mfma_f32_16x16x32_bf16 v[96:99], v[132:135], v[4:7], v[96:99]
	v_mfma_f32_16x16x32_bf16 v[112:115], v[132:135], v[20:23], v[112:115]
	v_mfma_f32_16x16x32_bf16 v[96:99], v[136:139], v[8:11], v[96:99]
	v_mfma_f32_16x16x32_bf16 v[112:115], v[136:139], v[24:27], v[112:115]
	v_mfma_f32_16x16x32_bf16 v[96:99], v[140:143], v[12:15], v[96:99]
	v_mfma_f32_16x16x32_bf16 v[112:115], v[140:143], v[28:31], v[112:115]
	ds_read_b128 v[128:131], v178 offset:12288
	ds_read_b128 v[132:135], v179 offset:12288
	ds_read_b128 v[136:139], v180 offset:12288
	ds_read_b128 v[140:143], v181 offset:12288
	s_waitcnt lgkmcnt(8)
	v_mfma_f32_16x16x32_bf16 v[100:103], v[144:147], v[0:3], v[100:103]
	v_mfma_f32_16x16x32_bf16 v[116:119], v[144:147], v[16:19], v[116:119]
	v_mfma_f32_16x16x32_bf16 v[100:103], v[148:151], v[4:7], v[100:103]
	v_mfma_f32_16x16x32_bf16 v[116:119], v[148:151], v[20:23], v[116:119]
	v_mfma_f32_16x16x32_bf16 v[100:103], v[152:155], v[8:11], v[100:103]
	v_mfma_f32_16x16x32_bf16 v[116:119], v[152:155], v[24:27], v[116:119]
	v_mfma_f32_16x16x32_bf16 v[100:103], v[156:159], v[12:15], v[100:103]
	v_mfma_f32_16x16x32_bf16 v[116:119], v[156:159], v[28:31], v[116:119]
	s_waitcnt lgkmcnt(4)
	v_mfma_f32_16x16x32_bf16 v[104:107], v[202:205], v[0:3], v[104:107]
	v_mfma_f32_16x16x32_bf16 v[120:123], v[202:205], v[16:19], v[120:123]
	v_mfma_f32_16x16x32_bf16 v[104:107], v[206:209], v[4:7], v[104:107]
	v_mfma_f32_16x16x32_bf16 v[120:123], v[206:209], v[20:23], v[120:123]
	v_mfma_f32_16x16x32_bf16 v[104:107], v[210:213], v[8:11], v[104:107]
	v_mfma_f32_16x16x32_bf16 v[120:123], v[210:213], v[24:27], v[120:123]
	v_mfma_f32_16x16x32_bf16 v[104:107], v[214:217], v[12:15], v[104:107]
	v_mfma_f32_16x16x32_bf16 v[120:123], v[214:217], v[28:31], v[120:123]
	s_waitcnt lgkmcnt(0)
	v_mfma_f32_16x16x32_bf16 v[108:111], v[128:131], v[0:3], v[108:111]
	v_mfma_f32_16x16x32_bf16 v[124:127], v[128:131], v[16:19], v[124:127]
	v_mfma_f32_16x16x32_bf16 v[108:111], v[132:135], v[4:7], v[108:111]
	v_mfma_f32_16x16x32_bf16 v[124:127], v[132:135], v[20:23], v[124:127]
	v_mfma_f32_16x16x32_bf16 v[108:111], v[136:139], v[8:11], v[108:111]
	v_mfma_f32_16x16x32_bf16 v[124:127], v[136:139], v[24:27], v[124:127]
	v_mfma_f32_16x16x32_bf16 v[108:111], v[140:143], v[12:15], v[108:111]
	v_mfma_f32_16x16x32_bf16 v[124:127], v[140:143], v[28:31], v[124:127]
	ds_read_b64 v[128:129], v182
	ds_read_b64 v[130:131], v183
	ds_read_b64 v[132:133], v182 offset:2048
	ds_read_b64 v[134:135], v183 offset:2048
	ds_read_b64 v[136:137], v182 offset:4096
	ds_read_b64 v[138:139], v183 offset:4096
	ds_read_b64 v[140:141], v182 offset:6144
	ds_read_b64 v[142:143], v183 offset:6144
	ds_read_b64 v[144:145], v182 offset:8192
	ds_read_b64 v[146:147], v183 offset:8192
	ds_read_b64 v[148:149], v182 offset:10240
	ds_read_b64 v[150:151], v183 offset:10240
	ds_read_b64 v[152:153], v182 offset:12288
	ds_read_b64 v[154:155], v183 offset:12288
	ds_read_b64 v[156:157], v182 offset:14336
	ds_read_b64 v[158:159], v183 offset:14336
	v_max3_f32 v232, v96, v97, v98
	v_max3_f32 v234, v99, v100, v101
	v_max3_f32 v236, v102, v103, v104
	v_max3_f32 v232, v232, v105, v106
	v_max_f32_e32 v232, v232, v107
	v_max3_f32 v234, v234, v108, v109
	v_max_f32_e32 v234, v234, v110
	v_max_f32_e32 v236, v236, v111
	v_max3_f32 v232, v232, v234, v236
	v_max3_f32 v233, v112, v113, v114
	v_max3_f32 v235, v115, v116, v117
	v_max3_f32 v237, v118, v119, v120
	v_max3_f32 v233, v233, v121, v122
	v_max_f32_e32 v233, v233, v123
	v_max3_f32 v235, v235, v124, v125
	v_max_f32_e32 v235, v235, v126
	v_max_f32_e32 v237, v237, v127
	v_max3_f32 v233, v233, v235, v237
	v_mul_f32_e32 v232, s30, v232
	v_mul_f32_e32 v233, s30, v233
	v_sub_f32_e32 v236, v232, v222
	v_sub_f32_e32 v237, v233, v223
	v_max_f32_e32 v236, v236, v237
	v_cmp_lt_f32_e32 vcc, 0x41000000, v236
	s_cbranch_vccz .Lna_fast_ctx
; __device__ __forceinline__ unsigned pk2(float lo, float hi) { return __builtin_bit_cast(unsigned, __builtin_convertvector((f32x2){lo, hi}, hwbf16x2)); }
; __device__ __forceinline__ void phase_na(const Params& p, unsigned char* lds) {
;     ...
;                     mx = fmaxf(mx, __shfl_xor(mx, 16)); mx = fmaxf(mx, __shfl_xor(mx, 32));
;                     const bool resc = !__all(mx - mrow[mt] <= 8.0f);
;                     float mn = mrow[mt], alpha = 1.f;
;                     if (resc) { mn = fmaxf(mrow[mt], mx); alpha = __builtin_amdgcn_exp2f(mrow[mt] - mn); mrow[mt] = mn; }
;                     float ls = 0.f;
; #pragma unroll
;                     for (int nt = 0; nt < 4; ++nt) {
;                         const bool act = !band || (16 * nt < whi && 16 * nt + 16 > wlo);
;                         if (act) { const float p0 = __builtin_amdgcn_exp2f(st[mt][nt][0] - mn), p1 = __builtin_amdgcn_exp2f(st[mt][nt][1] - mn), p2 = __builtin_amdgcn_exp2f(st[mt][nt][2] - mn), p3 = __builtin_amdgcn_exp2f(st[mt][nt][3] - mn);
;                             ls += (p0 + p1) + (p2 + p3); pk[mt][nt][0] = pk2(p0, p1); pk[mt][nt][1] = pk2(p2, p3); }
;                         else { pk[mt][nt][0] = 0u; pk[mt][nt][1] = 0u; }
;                     }
;                     lrow[mt] = lrow[mt] * alpha + ls;
;                     if (resc) {
; #pragma unroll
;                         for (int dt = 0; dt < 8; ++dt) Oa[mt][dt] = Oa[mt][dt] * alpha; }
	ds_bpermute_b32 v234, v218, v232
	ds_bpermute_b32 v235, v218, v233
	s_waitcnt lgkmcnt(0)
	v_max_f32_e32 v232, v232, v234
	v_max_f32_e32 v233, v233, v235
	ds_bpermute_b32 v234, v219, v232
	ds_bpermute_b32 v235, v219, v233
	s_waitcnt lgkmcnt(0)
	v_max_f32_e32 v232, v232, v234
	v_max_f32_e32 v233, v233, v235
	v_max_f32_e32 v236, v222, v232
	v_sub_f32_e32 v237, v222, v236
	v_exp_f32_e32 v237, v237
	v_mov_b32_e32 v222, v236
	v_sub_f32_e32 v226, 0, v236
	v_mul_f32_e32 v224, v224, v237
	v_mul_f32_e32 v32, v32, v237
	v_mul_f32_e32 v33, v33, v237
	v_mul_f32_e32 v34, v34, v237
	v_mul_f32_e32 v35, v35, v237
	v_mul_f32_e32 v36, v36, v237
	v_mul_f32_e32 v37, v37, v237
	v_mul_f32_e32 v38, v38, v237
	v_mul_f32_e32 v39, v39, v237
	v_mul_f32_e32 v40, v40, v237
	v_mul_f32_e32 v41, v41, v237
	v_mul_f32_e32 v42, v42, v237
	v_mul_f32_e32 v43, v43, v237
	v_mul_f32_e32 v44, v44, v237
	v_mul_f32_e32 v45, v45, v237
	v_mul_f32_e32 v46, v46, v237
	v_mul_f32_e32 v47, v47, v237
	v_mul_f32_e32 v48, v48, v237
	v_mul_f32_e32 v49, v49, v237
	v_mul_f32_e32 v50, v50, v237
	v_mul_f32_e32 v51, v51, v237
	v_mul_f32_e32 v52, v52, v237
	v_mul_f32_e32 v53, v53, v237
	v_mul_f32_e32 v54, v54, v237
	v_mul_f32_e32 v55, v55, v237
	v_mul_f32_e32 v56, v56, v237
	v_mul_f32_e32 v57, v57, v237
	v_mul_f32_e32 v58, v58, v237
	v_mul_f32_e32 v59, v59, v237
	v_mul_f32_e32 v60, v60, v237
	v_mul_f32_e32 v61, v61, v237
	v_mul_f32_e32 v62, v62, v237
	v_mul_f32_e32 v63, v63, v237
	v_max_f32_e32 v236, v223, v233
	v_sub_f32_e32 v237, v223, v236
	v_exp_f32_e32 v237, v237
	v_mov_b32_e32 v223, v236
	v_sub_f32_e32 v227, 0, v236
	v_mul_f32_e32 v225, v225, v237
	v_mul_f32_e32 v64, v64, v237
	v_mul_f32_e32 v65, v65, v237
	v_mul_f32_e32 v66, v66, v237
	v_mul_f32_e32 v67, v67, v237
	v_mul_f32_e32 v68, v68, v237
	v_mul_f32_e32 v69, v69, v237
	v_mul_f32_e32 v70, v70, v237
	v_mul_f32_e32 v71, v71, v237
	v_mul_f32_e32 v72, v72, v237
	v_mul_f32_e32 v73, v73, v237
	v_mul_f32_e32 v74, v74, v237
	v_mul_f32_e32 v75, v75, v237
	v_mul_f32_e32 v76, v76, v237
	v_mul_f32_e32 v77, v77, v237
	v_mul_f32_e32 v78, v78, v237
	v_mul_f32_e32 v79, v79, v237
	v_mul_f32_e32 v80, v80, v237
	v_mul_f32_e32 v81, v81, v237
	v_mul_f32_e32 v82, v82, v237
	v_mul_f32_e32 v83, v83, v237
	v_mul_f32_e32 v84, v84, v237
	v_mul_f32_e32 v85, v85, v237
	v_mul_f32_e32 v86, v86, v237
	v_mul_f32_e32 v87, v87, v237
	v_mul_f32_e32 v88, v88, v237
	v_mul_f32_e32 v89, v89, v237
	v_mul_f32_e32 v90, v90, v237
	v_mul_f32_e32 v91, v91, v237
	v_mul_f32_e32 v92, v92, v237
	v_mul_f32_e32 v93, v93, v237
	v_mul_f32_e32 v94, v94, v237
	v_mul_f32_e32 v95, v95, v237
.Lna_fast_ctx:
	v_fma_f32 v96, v96, s30, v226
	v_fma_f32 v97, v97, s30, v226
	v_fma_f32 v98, v98, s30, v226
	v_fma_f32 v99, v99, s30, v226
	v_fma_f32 v100, v100, s30, v226
	v_fma_f32 v101, v101, s30, v226
	v_fma_f32 v102, v102, s30, v226
	v_fma_f32 v103, v103, s30, v226
	v_fma_f32 v104, v104, s30, v226
	v_fma_f32 v105, v105, s30, v226
	v_fma_f32 v106, v106, s30, v226
	v_fma_f32 v107, v107, s30, v226
	v_fma_f32 v108, v108, s30, v226
	v_fma_f32 v109, v109, s30, v226
	v_fma_f32 v110, v110, s30, v226
	v_fma_f32 v111, v111, s30, v226
	v_fma_f32 v112, v112, s30, v227
	v_fma_f32 v113, v113, s30, v227
	v_fma_f32 v114, v114, s30, v227
	v_fma_f32 v115, v115, s30, v227
	v_fma_f32 v116, v116, s30, v227
	v_fma_f32 v117, v117, s30, v227
	v_fma_f32 v118, v118, s30, v227
	v_fma_f32 v119, v119, s30, v227
	v_fma_f32 v120, v120, s30, v227
	v_fma_f32 v121, v121, s30, v227
	v_fma_f32 v122, v122, s30, v227
	v_fma_f32 v123, v123, s30, v227
	v_fma_f32 v124, v124, s30, v227
	v_fma_f32 v125, v125, s30, v227
	v_fma_f32 v126, v126, s30, v227
	v_fma_f32 v127, v127, s30, v227
	v_exp_f32_e32 v96, v96
	v_exp_f32_e32 v97, v97
	v_exp_f32_e32 v98, v98
	v_exp_f32_e32 v99, v99
	v_exp_f32_e32 v100, v100
	v_exp_f32_e32 v101, v101
	v_exp_f32_e32 v102, v102
	v_exp_f32_e32 v103, v103
	v_exp_f32_e32 v104, v104
	v_exp_f32_e32 v105, v105
	v_exp_f32_e32 v106, v106
	v_exp_f32_e32 v107, v107
	v_exp_f32_e32 v108, v108
	v_exp_f32_e32 v109, v109
	v_exp_f32_e32 v110, v110
	v_exp_f32_e32 v111, v111
	v_exp_f32_e32 v112, v112
	v_exp_f32_e32 v113, v113
	v_exp_f32_e32 v114, v114
	v_exp_f32_e32 v115, v115
	v_exp_f32_e32 v116, v116
	v_exp_f32_e32 v117, v117
	v_exp_f32_e32 v118, v118
	v_exp_f32_e32 v119, v119
	v_exp_f32_e32 v120, v120
	v_exp_f32_e32 v121, v121
	v_exp_f32_e32 v122, v122
	v_exp_f32_e32 v123, v123
	v_exp_f32_e32 v124, v124
	v_exp_f32_e32 v125, v125
	v_exp_f32_e32 v126, v126
	v_exp_f32_e32 v127, v127
	v_add_f32_e32 v232, v96, v97
	v_add_f32_e32 v232, v232, v98
	v_add_f32_e32 v232, v232, v99
	v_add_f32_e32 v232, v232, v100
	v_add_f32_e32 v232, v232, v101
	v_add_f32_e32 v232, v232, v102
	v_add_f32_e32 v232, v232, v103
	v_add_f32_e32 v232, v232, v104
	v_add_f32_e32 v232, v232, v105
	v_add_f32_e32 v232, v232, v106
	v_add_f32_e32 v232, v232, v107
	v_add_f32_e32 v232, v232, v108
	v_add_f32_e32 v232, v232, v109
	v_add_f32_e32 v232, v232, v110
	v_add_f32_e32 v232, v232, v111
	v_add_f32_e32 v224, v224, v232
	v_add_f32_e32 v233, v112, v113
	v_add_f32_e32 v233, v233, v114
	v_add_f32_e32 v233, v233, v115
	v_add_f32_e32 v233, v233, v116
	v_add_f32_e32 v233, v233, v117
	v_add_f32_e32 v233, v233, v118
	v_add_f32_e32 v233, v233, v119
	v_add_f32_e32 v233, v233, v120
	v_add_f32_e32 v233, v233, v121
	v_add_f32_e32 v233, v233, v122
	v_add_f32_e32 v233, v233, v123
	v_add_f32_e32 v233, v233, v124
	v_add_f32_e32 v233, v233, v125
	v_add_f32_e32 v233, v233, v126
	v_add_f32_e32 v233, v233, v127
	v_add_f32_e32 v225, v225, v233
	v_cvt_pk_bf16_f32 v96, v96, v97
	v_cvt_pk_bf16_f32 v97, v98, v99
	v_cvt_pk_bf16_f32 v98, v100, v101
	v_cvt_pk_bf16_f32 v99, v102, v103
	v_cvt_pk_bf16_f32 v104, v104, v105
	v_cvt_pk_bf16_f32 v105, v106, v107
	v_cvt_pk_bf16_f32 v106, v108, v109
	v_cvt_pk_bf16_f32 v107, v110, v111
	v_cvt_pk_bf16_f32 v112, v112, v113
	v_cvt_pk_bf16_f32 v113, v114, v115
	v_cvt_pk_bf16_f32 v114, v116, v117
	v_cvt_pk_bf16_f32 v115, v118, v119
	v_cvt_pk_bf16_f32 v120, v120, v121
	v_cvt_pk_bf16_f32 v121, v122, v123
	v_cvt_pk_bf16_f32 v122, v124, v125
	v_cvt_pk_bf16_f32 v123, v126, v127
	s_waitcnt lgkmcnt(0)
; __device__ __forceinline__ void phase_na(const Params& p, unsigned char* lds) {
;     ...
;                 __builtin_amdgcn_sched_barrier(0);
; #pragma unroll
;                 for (int kk = 0; kk < 2; ++kk) {
;                     const int ta = 2 * kk, tb = 2 * kk + 1;
;                     const bf16x8 Bp0 = as_bf16x8((u32x4){pk[0][ta][0], pk[0][ta][1], pk[0][tb][0], pk[0][tb][1]}), Bp1 = as_bf16x8((u32x4){pk[1][ta][0], pk[1][ta][1], pk[1][tb][0], pk[1][tb][1]});
; #pragma unroll
;                     for (int dt = 0; dt < 8; ++dt) {
;                         const u32x2 va = *(const u32x2*)(vt + (dt * 16 + fr) * 72 + 16 * ta + fq * 4), vb = *(const u32x2*)(vt + (dt * 16 + fr) * 72 + 16 * tb + fq * 4);
;                         const bf16x8 Av = as_bf16x8((u32x4){va.x, va.y, vb.x, vb.y});
;                         Oa[0][dt] = __builtin_amdgcn_mfma_f32_16x16x32_bf16(Av, Bp0, Oa[0][dt], 0, 0, 0);
;                         Oa[1][dt] = __builtin_amdgcn_mfma_f32_16x16x32_bf16(Av, Bp1, Oa[1][dt], 0, 0, 0); }
;                     __builtin_amdgcn_sched_group_barrier(0x100, 8, 0);
; #pragma unroll
;                     for (int q = 0; q < 4; ++q) { __builtin_amdgcn_sched_group_barrier(0x008, 2, 0); __builtin_amdgcn_sched_group_barrier(0x100, 2, 0); }
;                     __builtin_amdgcn_sched_group_barrier(0x008, 8, 0);
;                     __builtin_amdgcn_sched_barrier(0);
;                 }
;             }
;             __syncthreads();
	s_nop 1
	v_mfma_f32_16x16x32_bf16 v[32:35], v[128:131], v[96:99], v[32:35]
	v_mfma_f32_16x16x32_bf16 v[64:67], v[128:131], v[112:115], v[64:67]
	v_mfma_f32_16x16x32_bf16 v[36:39], v[132:135], v[96:99], v[36:39]
	v_mfma_f32_16x16x32_bf16 v[68:71], v[132:135], v[112:115], v[68:71]
	v_mfma_f32_16x16x32_bf16 v[40:43], v[136:139], v[96:99], v[40:43]
	v_mfma_f32_16x16x32_bf16 v[72:75], v[136:139], v[112:115], v[72:75]
	v_mfma_f32_16x16x32_bf16 v[44:47], v[140:143], v[96:99], v[44:47]
	v_mfma_f32_16x16x32_bf16 v[76:79], v[140:143], v[112:115], v[76:79]
	ds_read_b64 v[128:129], v184
	ds_read_b64 v[130:131], v185
	ds_read_b64 v[132:133], v184 offset:2048
	ds_read_b64 v[134:135], v185 offset:2048
	ds_read_b64 v[136:137], v184 offset:4096
	ds_read_b64 v[138:139], v185 offset:4096
	ds_read_b64 v[140:141], v184 offset:6144
	ds_read_b64 v[142:143], v185 offset:6144
	v_mfma_f32_16x16x32_bf16 v[48:51], v[144:147], v[96:99], v[48:51]
	v_mfma_f32_16x16x32_bf16 v[80:83], v[144:147], v[112:115], v[80:83]
	v_mfma_f32_16x16x32_bf16 v[52:55], v[148:151], v[96:99], v[52:55]
	v_mfma_f32_16x16x32_bf16 v[84:87], v[148:151], v[112:115], v[84:87]
	v_mfma_f32_16x16x32_bf16 v[56:59], v[152:155], v[96:99], v[56:59]
	v_mfma_f32_16x16x32_bf16 v[88:91], v[152:155], v[112:115], v[88:91]
	v_mfma_f32_16x16x32_bf16 v[60:63], v[156:159], v[96:99], v[60:63]
	v_mfma_f32_16x16x32_bf16 v[92:95], v[156:159], v[112:115], v[92:95]
	ds_read_b64 v[144:145], v184 offset:8192
	ds_read_b64 v[146:147], v185 offset:8192
	ds_read_b64 v[148:149], v184 offset:10240
	ds_read_b64 v[150:151], v185 offset:10240
	ds_read_b64 v[152:153], v184 offset:12288
	ds_read_b64 v[154:155], v185 offset:12288
	ds_read_b64 v[156:157], v184 offset:14336
	ds_read_b64 v[158:159], v185 offset:14336
	s_waitcnt lgkmcnt(8)
	v_mfma_f32_16x16x32_bf16 v[32:35], v[128:131], v[104:107], v[32:35]
	v_mfma_f32_16x16x32_bf16 v[64:67], v[128:131], v[120:123], v[64:67]
	v_mfma_f32_16x16x32_bf16 v[36:39], v[132:135], v[104:107], v[36:39]
	v_mfma_f32_16x16x32_bf16 v[68:71], v[132:135], v[120:123], v[68:71]
	v_mfma_f32_16x16x32_bf16 v[40:43], v[136:139], v[104:107], v[40:43]
	v_mfma_f32_16x16x32_bf16 v[72:75], v[136:139], v[120:123], v[72:75]
	v_mfma_f32_16x16x32_bf16 v[44:47], v[140:143], v[104:107], v[44:47]
	v_mfma_f32_16x16x32_bf16 v[76:79], v[140:143], v[120:123], v[76:79]
	s_waitcnt lgkmcnt(0)
	v_mfma_f32_16x16x32_bf16 v[48:51], v[144:147], v[104:107], v[48:51]
	v_mfma_f32_16x16x32_bf16 v[80:83], v[144:147], v[120:123], v[80:83]
	v_mfma_f32_16x16x32_bf16 v[52:55], v[148:151], v[104:107], v[52:55]
	v_mfma_f32_16x16x32_bf16 v[84:87], v[148:151], v[120:123], v[84:87]
	v_mfma_f32_16x16x32_bf16 v[56:59], v[152:155], v[104:107], v[56:59]
	v_mfma_f32_16x16x32_bf16 v[88:91], v[152:155], v[120:123], v[88:91]
	v_mfma_f32_16x16x32_bf16 v[60:63], v[156:159], v[104:107], v[60:63]
	v_mfma_f32_16x16x32_bf16 v[92:95], v[156:159], v[120:123], v[92:95]
	s_branch .Lna_after
.Lna_after:
.Lna_tile_end:
	s_add_i32 s22, s21, 2
	s_cmp_ge_u32 s22, s18
	s_cbranch_scc1 .Lna_e0
	s_waitcnt vmcnt(4)
	s_branch .Lna_e1
.Lna_e0:
	s_waitcnt vmcnt(0)
; __device__ __forceinline__ unsigned pk2(float lo, float hi) { return __builtin_bit_cast(unsigned, __builtin_convertvector((f32x2){lo, hi}, hwbf16x2)); }
; __device__ __forceinline__ void phase_na(const Params& p, unsigned char* lds) {
;     ...
;             __syncthreads();
;         }
;         { bf16_t* ost = KtB + w * (32 * 136);
; #pragma unroll
;           for (int mt = 0; mt < 2; ++mt) {
;             float l = lrow[mt]; l += __shfl_xor(l, 16); l += __shfl_xor(l, 32); const float inv = 1.f / l;
; #pragma unroll
;             for (int dt = 0; dt < 8; ++dt) *(u32x2*)(ost + (mt * 16 + fr) * 136 + dt * 16 + fq * 4) = (u32x2){pk2(Oa[mt][dt][0] * inv, Oa[mt][dt][1] * inv), pk2(Oa[mt][dt][2] * inv, Oa[mt][dt][3] * inv)}; }
;           asm volatile("s_waitcnt lgkmcnt(0)" ::: "memory");
;           const int q = lane >> 1, hf = lane & 1;
;           bf16_t* op = O + (size_t)(b * SEQ + qr * 64 + qc0 + q) * D + h * 128 + hf * 64;
; #pragma unroll
;           for (int e = 0; e < 8; ++e) *(u32x4*)(op + e * 8) = *(const u32x4*)(ost + q * 136 + hf * 64 + e * 8); }
.Lna_e1:
	s_waitcnt lgkmcnt(0)
	s_barrier
	s_mov_b32 s65, s66
	s_add_i32 s66, s66, 1
	s_cmp_eq_u32 s66, 3
	s_cselect_b32 s66, 0, s66
	s_add_i32 s21, s21, 1
	s_cmp_lt_u32 s21, s18
	s_cbranch_scc1 .Lna_tile
	ds_bpermute_b32 v232, v218, v224
	ds_bpermute_b32 v233, v218, v225
	s_waitcnt lgkmcnt(0)
	v_add_f32_e32 v232, v232, v224
	v_add_f32_e32 v233, v233, v225
	ds_bpermute_b32 v234, v219, v232
	ds_bpermute_b32 v235, v219, v233
	s_waitcnt lgkmcnt(0)
	v_add_f32_e32 v232, v232, v234
	v_add_f32_e32 v233, v233, v235
	v_rcp_f32_e32 v234, v232
	s_nop 0
	v_fma_f32 v236, -v232, v234, 1.0
	v_fma_f32 v234, v236, v234, v234
	v_rcp_f32_e32 v235, v233
	s_nop 0
	v_fma_f32 v237, -v233, v235, 1.0
	v_fma_f32 v235, v237, v235, v235
	s_mul_i32 s0, s10, 0x2200
	v_and_b32_e32 v238, 15, v162
	v_mul_u32_u24_e32 v238, 0x110, v238
	v_bfe_u32 v239, v162, 4, 2
	v_lshl_add_u32 v238, v239, 3, v238
	v_add_u32_e32 v238, s0, v238
	v_mul_f32_e32 v32, v32, v234
	v_mul_f32_e32 v33, v33, v234
	v_mul_f32_e32 v34, v34, v234
	v_mul_f32_e32 v35, v35, v234
	v_cvt_pk_bf16_f32 v32, v32, v33
	v_cvt_pk_bf16_f32 v33, v34, v35
	ds_write_b64 v238, v[32:33] offset:0
	v_mul_f32_e32 v36, v36, v234
	v_mul_f32_e32 v37, v37, v234
	v_mul_f32_e32 v38, v38, v234
	v_mul_f32_e32 v39, v39, v234
	v_cvt_pk_bf16_f32 v36, v36, v37
	v_cvt_pk_bf16_f32 v37, v38, v39
	ds_write_b64 v238, v[36:37] offset:32
	v_mul_f32_e32 v40, v40, v234
	v_mul_f32_e32 v41, v41, v234
	v_mul_f32_e32 v42, v42, v234
	v_mul_f32_e32 v43, v43, v234
	v_cvt_pk_bf16_f32 v40, v40, v41
	v_cvt_pk_bf16_f32 v41, v42, v43
	ds_write_b64 v238, v[40:41] offset:64
	v_mul_f32_e32 v44, v44, v234
	v_mul_f32_e32 v45, v45, v234
	v_mul_f32_e32 v46, v46, v234
	v_mul_f32_e32 v47, v47, v234
	v_cvt_pk_bf16_f32 v44, v44, v45
	v_cvt_pk_bf16_f32 v45, v46, v47
	ds_write_b64 v238, v[44:45] offset:96
	v_mul_f32_e32 v48, v48, v234
	v_mul_f32_e32 v49, v49, v234
	v_mul_f32_e32 v50, v50, v234
	v_mul_f32_e32 v51, v51, v234
	v_cvt_pk_bf16_f32 v48, v48, v49
	v_cvt_pk_bf16_f32 v49, v50, v51
	ds_write_b64 v238, v[48:49] offset:128
	v_mul_f32_e32 v52, v52, v234
	v_mul_f32_e32 v53, v53, v234
	v_mul_f32_e32 v54, v54, v234
	v_mul_f32_e32 v55, v55, v234
	v_cvt_pk_bf16_f32 v52, v52, v53
	v_cvt_pk_bf16_f32 v53, v54, v55
	ds_write_b64 v238, v[52:53] offset:160
	v_mul_f32_e32 v56, v56, v234
	v_mul_f32_e32 v57, v57, v234
	v_mul_f32_e32 v58, v58, v234
	v_mul_f32_e32 v59, v59, v234
	v_cvt_pk_bf16_f32 v56, v56, v57
	v_cvt_pk_bf16_f32 v57, v58, v59
	ds_write_b64 v238, v[56:57] offset:192
	v_mul_f32_e32 v60, v60, v234
	v_mul_f32_e32 v61, v61, v234
	v_mul_f32_e32 v62, v62, v234
	v_mul_f32_e32 v63, v63, v234
	v_cvt_pk_bf16_f32 v60, v60, v61
	v_cvt_pk_bf16_f32 v61, v62, v63
	ds_write_b64 v238, v[60:61] offset:224
	v_mul_f32_e32 v64, v64, v235
	v_mul_f32_e32 v65, v65, v235
	v_mul_f32_e32 v66, v66, v235
	v_mul_f32_e32 v67, v67, v235
	v_cvt_pk_bf16_f32 v64, v64, v65
	v_cvt_pk_bf16_f32 v65, v66, v67
	ds_write_b64 v238, v[64:65] offset:4352
	v_mul_f32_e32 v68, v68, v235
	v_mul_f32_e32 v69, v69, v235
	v_mul_f32_e32 v70, v70, v235
	v_mul_f32_e32 v71, v71, v235
	v_cvt_pk_bf16_f32 v68, v68, v69
	v_cvt_pk_bf16_f32 v69, v70, v71
	ds_write_b64 v238, v[68:69] offset:4384
	v_mul_f32_e32 v72, v72, v235
	v_mul_f32_e32 v73, v73, v235
	v_mul_f32_e32 v74, v74, v235
	v_mul_f32_e32 v75, v75, v235
	v_cvt_pk_bf16_f32 v72, v72, v73
	v_cvt_pk_bf16_f32 v73, v74, v75
	ds_write_b64 v238, v[72:73] offset:4416
	v_mul_f32_e32 v76, v76, v235
	v_mul_f32_e32 v77, v77, v235
	v_mul_f32_e32 v78, v78, v235
	v_mul_f32_e32 v79, v79, v235
	v_cvt_pk_bf16_f32 v76, v76, v77
	v_cvt_pk_bf16_f32 v77, v78, v79
	ds_write_b64 v238, v[76:77] offset:4448
	v_mul_f32_e32 v80, v80, v235
	v_mul_f32_e32 v81, v81, v235
	v_mul_f32_e32 v82, v82, v235
	v_mul_f32_e32 v83, v83, v235
	v_cvt_pk_bf16_f32 v80, v80, v81
	v_cvt_pk_bf16_f32 v81, v82, v83
	ds_write_b64 v238, v[80:81] offset:4480
	v_mul_f32_e32 v84, v84, v235
	v_mul_f32_e32 v85, v85, v235
	v_mul_f32_e32 v86, v86, v235
	v_mul_f32_e32 v87, v87, v235
	v_cvt_pk_bf16_f32 v84, v84, v85
	v_cvt_pk_bf16_f32 v85, v86, v87
	ds_write_b64 v238, v[84:85] offset:4512
	v_mul_f32_e32 v88, v88, v235
	v_mul_f32_e32 v89, v89, v235
	v_mul_f32_e32 v90, v90, v235
	v_mul_f32_e32 v91, v91, v235
	v_cvt_pk_bf16_f32 v88, v88, v89
	v_cvt_pk_bf16_f32 v89, v90, v91
	ds_write_b64 v238, v[88:89] offset:4544
	v_mul_f32_e32 v92, v92, v235
	v_mul_f32_e32 v93, v93, v235
	v_mul_f32_e32 v94, v94, v235
	v_mul_f32_e32 v95, v95, v235
	v_cvt_pk_bf16_f32 v92, v92, v93
	v_cvt_pk_bf16_f32 v93, v94, v95
	ds_write_b64 v238, v[92:93] offset:4576
	s_waitcnt lgkmcnt(0)
	v_and_b32_e32 v232, 63, v162
	v_lshrrev_b32_e32 v233, 1, v232
	v_and_b32_e32 v234, 1, v232
	v_mul_u32_u24_e32 v235, 0x110, v233
	v_lshl_add_u32 v235, v234, 7, v235
	v_add_u32_e32 v235, s0, v235
	ds_read_b128 v[128:131], v235 offset:0
	ds_read_b128 v[132:135], v235 offset:16
	ds_read_b128 v[136:139], v235 offset:32
	ds_read_b128 v[140:143], v235 offset:48
	ds_read_b128 v[144:147], v235 offset:64
	ds_read_b128 v[148:151], v235 offset:80
	ds_read_b128 v[152:155], v235 offset:96
	ds_read_b128 v[156:159], v235 offset:112
	s_lshl_b32 s0, s15, 12
	s_lshl_b32 s1, s19, 6
	s_add_i32 s0, s0, s1
	s_add_i32 s0, s0, s12
	v_add_u32_e32 v233, s0, v233
	v_lshlrev_b32_e32 v233, 12, v233
	v_lshl_add_u32 v233, v234, 7, v233
	s_lshl_b32 s1, s14, 8
	v_add_u32_e32 v233, s1, v233
	s_waitcnt lgkmcnt(7)
	global_store_dwordx4 v233, v[128:131], s[8:9] offset:0
	s_waitcnt lgkmcnt(6)
	global_store_dwordx4 v233, v[132:135], s[8:9] offset:16
	s_waitcnt lgkmcnt(5)
	global_store_dwordx4 v233, v[136:139], s[8:9] offset:32
	s_waitcnt lgkmcnt(4)
	global_store_dwordx4 v233, v[140:143], s[8:9] offset:48
	s_waitcnt lgkmcnt(3)
	global_store_dwordx4 v233, v[144:147], s[8:9] offset:64
	s_waitcnt lgkmcnt(2)
	global_store_dwordx4 v233, v[148:151], s[8:9] offset:80
	s_waitcnt lgkmcnt(1)
	global_store_dwordx4 v233, v[152:155], s[8:9] offset:96
	s_waitcnt lgkmcnt(0)
	global_store_dwordx4 v233, v[156:159], s[8:9] offset:112
	s_add_i32 s13, s13, s82
	s_branch .Lna_unit
